# v8 + responsibility-split L2 prefetch: one dword LDS-DMA touch per wave per iteration (24 lanes), each CU touches its 1/4 of the A-tile lines and 1/8 of the B-tile lines of K-tiles t+3,t+4
# speedup vs baseline: 1.0071x; 1.0016x over previous
.LBB0_340:
	s_and_b32 s98, s55, 3
	s_and_b32 s99, s54, 7
	s_lshl_b32 s98, s98, 6
	s_lshl_b32 s99, s99, 5
	v_and_b32_e32 v244, 63, v0
	v_mul_u32_u24_e32 v245, 43, v244
	v_lshrrev_b32_e32 v245, 10, v245
	v_mul_u32_u24_e32 v245, 24, v245
	v_sub_u32_e32 v244, v244, v245
	v_lshrrev_b32_e32 v245, 6, v0
	v_mad_u32_u24 v244, v245, 24, v244
	v_cmp_gt_u32_e32 vcc, 0x80, v244
	v_and_b32_e32 v245, 63, v244
	v_add_u32_e32 v245, s98, v245
	v_lshrrev_b32_e32 v246, 6, v244
	v_subrev_u32_e32 v247, 0x80, v244
	v_and_b32_e32 v248, 31, v247
	v_add_u32_e32 v248, s99, v248
	v_lshrrev_b32_e32 v247, 5, v247
	v_cndmask_b32_e32 v245, v248, v245, vcc
	v_cndmask_b32_e32 v246, v247, v246, vcc
	v_lshlrev_b32_e32 v245, 13, v245
	v_lshl_add_u32 v245, v246, 7, v245
	v_add_u32_e32 v244, 0x80, v245
	v_mov_b32_e32 v245, 0
	v_mov_b32_e32 v246, s12
	v_mov_b32_e32 v247, s13
	v_mov_b32_e32 v248, s14
	v_mov_b32_e32 v249, s15
	v_cndmask_b32_e32 v246, v248, v246, vcc
	v_cndmask_b32_e32 v247, v249, v247, vcc
	v_lshl_add_u64 v[242:243], v[246:247], 0, v[244:245]
	v_add_u32_e32 v252, 0x10000, v159
	s_add_u32 s12, s12, 0x100080
	s_addc_u32 s13, s13, 0
	s_add_u32 s0, s14, 0x100
	v_mov_b32_e32 v2, 0
	s_addc_u32 s1, s15, 0
	s_mov_b32 s39, -2
	v_mov_b32_e32 v3, v2
	v_mov_b32_e32 v4, v2
	v_mov_b32_e32 v5, v2
	v_mov_b32_e32 v6, v2
	v_mov_b32_e32 v7, v2
	v_mov_b32_e32 v8, v2
	v_mov_b32_e32 v9, v2
	v_mov_b32_e32 v18, v2
	v_mov_b32_e32 v19, v2
	v_mov_b32_e32 v20, v2
	v_mov_b32_e32 v21, v2
	v_mov_b32_e32 v22, v2
	v_mov_b32_e32 v23, v2
	v_mov_b32_e32 v24, v2
	v_mov_b32_e32 v25, v2
	v_mov_b32_e32 v34, v2
	v_mov_b32_e32 v35, v2
	v_mov_b32_e32 v36, v2
	v_mov_b32_e32 v37, v2
	v_mov_b32_e32 v38, v2
	v_mov_b32_e32 v39, v2
	v_mov_b32_e32 v40, v2
	v_mov_b32_e32 v41, v2
	v_mov_b32_e32 v50, v2
	v_mov_b32_e32 v51, v2
	v_mov_b32_e32 v52, v2
	v_mov_b32_e32 v53, v2
	v_mov_b32_e32 v54, v2
	v_mov_b32_e32 v55, v2
	v_mov_b32_e32 v56, v2
	v_mov_b32_e32 v57, v2
	v_mov_b32_e32 v10, v2
	v_mov_b32_e32 v11, v2
	v_mov_b32_e32 v12, v2
	v_mov_b32_e32 v13, v2
	v_mov_b32_e32 v14, v2
	v_mov_b32_e32 v15, v2
	v_mov_b32_e32 v16, v2
	v_mov_b32_e32 v17, v2
	v_mov_b32_e32 v26, v2
	v_mov_b32_e32 v27, v2
	v_mov_b32_e32 v28, v2
	v_mov_b32_e32 v29, v2
	v_mov_b32_e32 v30, v2
	v_mov_b32_e32 v31, v2
	v_mov_b32_e32 v32, v2
	v_mov_b32_e32 v33, v2
	v_mov_b32_e32 v42, v2
	v_mov_b32_e32 v43, v2
	v_mov_b32_e32 v44, v2
	v_mov_b32_e32 v45, v2
	v_mov_b32_e32 v46, v2
	v_mov_b32_e32 v47, v2
	v_mov_b32_e32 v48, v2
	v_mov_b32_e32 v49, v2
	v_mov_b32_e32 v58, v2
	v_mov_b32_e32 v59, v2
	v_mov_b32_e32 v60, v2
	v_mov_b32_e32 v61, v2
	v_mov_b32_e32 v62, v2
	v_mov_b32_e32 v63, v2
	v_mov_b32_e32 v64, v2
	v_mov_b32_e32 v65, v2
	v_mov_b32_e32 v66, v2
	v_mov_b32_e32 v67, v2
	v_mov_b32_e32 v68, v2
	v_mov_b32_e32 v69, v2
	v_mov_b32_e32 v70, v2
	v_mov_b32_e32 v71, v2
	v_mov_b32_e32 v72, v2
	v_mov_b32_e32 v73, v2
	v_mov_b32_e32 v82, v2
	v_mov_b32_e32 v83, v2
	v_mov_b32_e32 v84, v2
	v_mov_b32_e32 v85, v2
	v_mov_b32_e32 v86, v2
	v_mov_b32_e32 v87, v2
	v_mov_b32_e32 v88, v2
	v_mov_b32_e32 v89, v2
	v_mov_b32_e32 v98, v2
	v_mov_b32_e32 v99, v2
	v_mov_b32_e32 v100, v2
	v_mov_b32_e32 v101, v2
	v_mov_b32_e32 v102, v2
	v_mov_b32_e32 v103, v2
	v_mov_b32_e32 v104, v2
	v_mov_b32_e32 v105, v2
	v_mov_b32_e32 v114, v2
	v_mov_b32_e32 v115, v2
	v_mov_b32_e32 v116, v2
	v_mov_b32_e32 v117, v2
	v_mov_b32_e32 v118, v2
	v_mov_b32_e32 v119, v2
	v_mov_b32_e32 v120, v2
	v_mov_b32_e32 v121, v2
	v_mov_b32_e32 v74, v2
	v_mov_b32_e32 v75, v2
	v_mov_b32_e32 v76, v2
	v_mov_b32_e32 v77, v2
	v_mov_b32_e32 v78, v2
	v_mov_b32_e32 v79, v2
	v_mov_b32_e32 v80, v2
	v_mov_b32_e32 v81, v2
	v_mov_b32_e32 v90, v2
	v_mov_b32_e32 v91, v2
	v_mov_b32_e32 v92, v2
	v_mov_b32_e32 v93, v2
	v_mov_b32_e32 v94, v2
	v_mov_b32_e32 v95, v2
	v_mov_b32_e32 v96, v2
	v_mov_b32_e32 v97, v2
	v_mov_b32_e32 v106, v2
	v_mov_b32_e32 v107, v2
	v_mov_b32_e32 v108, v2
	v_mov_b32_e32 v109, v2
	v_mov_b32_e32 v110, v2
	v_mov_b32_e32 v111, v2
	v_mov_b32_e32 v112, v2
	v_mov_b32_e32 v113, v2
	v_mov_b32_e32 v122, v2
	v_mov_b32_e32 v123, v2
	v_mov_b32_e32 v124, v2
	v_mov_b32_e32 v125, v2
	v_mov_b32_e32 v126, v2
	v_mov_b32_e32 v127, v2
	v_mov_b32_e32 v128, v2
	v_mov_b32_e32 v129, v2
.LBB0_341:
	s_add_u32 s14, s12, 0xfff00080
	s_addc_u32 s15, s13, -1
	s_cmp_eq_u32 s39, 60
	s_cselect_b32 s17, s51, s15
	s_cselect_b32 s16, s50, s14
	s_cselect_b32 s15, s53, s1
	s_cselect_b32 s14, s52, s0
	s_cmp_lt_i32 s39, 57
	s_cselect_b32 s100, 0x100, 0
	s_mov_b32 s101, 0
	v_lshl_add_u64 v[242:243], v[242:243], 0, s[100:101]
	s_add_i32 m0, s8, 0xc000
	ds_read_b128 v[152:155], v252
	ds_read_b128 v[162:165], v252 offset:1024
	global_load_lds_dwordx4 v148, s[12:13]
	s_add_i32 m0, s8, 0xe000
	ds_read_b128 v[166:169], v252 offset:2048
	ds_read_b128 v[170:173], v252 offset:3072
	global_load_lds_dwordx4 v150, s[12:13]
	ds_read_b128 v[174:177], v252 offset:16384
	ds_read_b128 v[182:185], v252 offset:17408
	ds_read_b128 v[186:189], v252 offset:18432
	ds_read_b128 v[190:193], v252 offset:19456
	ds_read_b128 v[194:197], v161
	ds_read_b128 v[198:201], v161 offset:1024
	ds_read_b128 v[202:205], v161 offset:2048
	ds_read_b128 v[206:209], v161 offset:3072
	ds_read_b128 v[210:213], v161 offset:4096
	ds_read_b128 v[214:217], v161 offset:5120
	ds_read_b128 v[218:221], v161 offset:6144
	ds_read_b128 v[222:225], v161 offset:7168
	s_waitcnt vmcnt(8)
	s_mov_b32 m0, 0x21800
	s_mov_b64 exec, 0xffffff
	s_waitcnt lgkmcnt(0)
	global_load_lds_dword v[242:243], off
	s_mov_b64 exec, -1
	s_barrier
	v_mfma_f32_16x16x32_bf16 v[126:129], v[152:155], v[194:197], v[126:129]
	v_mfma_f32_16x16x32_bf16 v[126:129], v[162:165], v[198:201], v[126:129]
	v_mfma_f32_16x16x32_bf16 v[122:125], v[166:169], v[194:197], v[122:125]
	v_mfma_f32_16x16x32_bf16 v[122:125], v[170:173], v[198:201], v[122:125]
	v_mfma_f32_16x16x32_bf16 v[110:113], v[152:155], v[202:205], v[110:113]
	v_mfma_f32_16x16x32_bf16 v[110:113], v[162:165], v[206:209], v[110:113]
	v_mfma_f32_16x16x32_bf16 v[106:109], v[166:169], v[202:205], v[106:109]
	v_mfma_f32_16x16x32_bf16 v[106:109], v[170:173], v[206:209], v[106:109]
	v_mfma_f32_16x16x32_bf16 v[94:97], v[152:155], v[210:213], v[94:97]
	v_mfma_f32_16x16x32_bf16 v[94:97], v[162:165], v[214:217], v[94:97]
	v_mfma_f32_16x16x32_bf16 v[90:93], v[166:169], v[210:213], v[90:93]
	v_mfma_f32_16x16x32_bf16 v[90:93], v[170:173], v[214:217], v[90:93]
	v_mfma_f32_16x16x32_bf16 v[78:81], v[152:155], v[218:221], v[78:81]
	v_mfma_f32_16x16x32_bf16 v[78:81], v[162:165], v[222:225], v[78:81]
	v_mfma_f32_16x16x32_bf16 v[74:77], v[166:169], v[218:221], v[74:77]
	v_mfma_f32_16x16x32_bf16 v[74:77], v[170:173], v[222:225], v[74:77]
	v_mfma_f32_16x16x32_bf16 v[118:121], v[174:177], v[194:197], v[118:121]
	v_mfma_f32_16x16x32_bf16 v[118:121], v[182:185], v[198:201], v[118:121]
	v_mfma_f32_16x16x32_bf16 v[114:117], v[186:189], v[194:197], v[114:117]
	v_mfma_f32_16x16x32_bf16 v[114:117], v[190:193], v[198:201], v[114:117]
	v_mfma_f32_16x16x32_bf16 v[102:105], v[174:177], v[202:205], v[102:105]
	v_mfma_f32_16x16x32_bf16 v[102:105], v[182:185], v[206:209], v[102:105]
	v_mfma_f32_16x16x32_bf16 v[98:101], v[186:189], v[202:205], v[98:101]
	v_mfma_f32_16x16x32_bf16 v[98:101], v[190:193], v[206:209], v[98:101]
	v_mfma_f32_16x16x32_bf16 v[86:89], v[174:177], v[210:213], v[86:89]
	v_mfma_f32_16x16x32_bf16 v[86:89], v[182:185], v[214:217], v[86:89]
	v_mfma_f32_16x16x32_bf16 v[82:85], v[186:189], v[210:213], v[82:85]
	v_mfma_f32_16x16x32_bf16 v[82:85], v[190:193], v[214:217], v[82:85]
	v_mfma_f32_16x16x32_bf16 v[70:73], v[174:177], v[218:221], v[70:73]
	v_mfma_f32_16x16x32_bf16 v[70:73], v[182:185], v[222:225], v[70:73]
	v_mfma_f32_16x16x32_bf16 v[66:69], v[186:189], v[218:221], v[66:69]
	v_mfma_f32_16x16x32_bf16 v[66:69], v[190:193], v[222:225], v[66:69]
	s_barrier
	s_add_i32 m0, s28, 0x10000
	ds_read_b128 v[194:197], v161 offset:16384
	ds_read_b128 v[198:201], v161 offset:17408
	global_load_lds_dwordx4 v144, s[14:15]
	s_add_i32 m0, s28, 0x12000
	s_add_u32 s98, s14, 0x100000
	s_addc_u32 s99, s15, 0
	ds_read_b128 v[202:205], v161 offset:18432
	global_load_lds_dwordx4 v140, s[14:15]
	s_add_i32 m0, s28, 0x14000
	ds_read_b128 v[206:209], v161 offset:19456
	ds_read_b128 v[210:213], v161 offset:20480
	global_load_lds_dwordx4 v144, s[98:99]
	s_add_i32 m0, s28, 0x16000
	ds_read_b128 v[214:217], v161 offset:21504
	ds_read_b128 v[218:221], v161 offset:22528
	global_load_lds_dwordx4 v140, s[98:99]
	s_mov_b32 m0, s8
	ds_read_b128 v[222:225], v161 offset:23552
	global_load_lds_dwordx4 v146, s[16:17]
	s_mov_b32 m0, s9
	s_nop 0
	global_load_lds_dwordx4 v142, s[16:17]
	s_waitcnt vmcnt(9)
	s_waitcnt lgkmcnt(0)
	s_barrier
	v_mfma_f32_16x16x32_bf16 v[62:65], v[152:155], v[194:197], v[62:65]
	v_mfma_f32_16x16x32_bf16 v[62:65], v[162:165], v[198:201], v[62:65]
	v_mfma_f32_16x16x32_bf16 v[58:61], v[166:169], v[194:197], v[58:61]
	v_mfma_f32_16x16x32_bf16 v[58:61], v[170:173], v[198:201], v[58:61]
	v_mfma_f32_16x16x32_bf16 v[46:49], v[152:155], v[202:205], v[46:49]
	v_mfma_f32_16x16x32_bf16 v[46:49], v[162:165], v[206:209], v[46:49]
	v_mfma_f32_16x16x32_bf16 v[42:45], v[166:169], v[202:205], v[42:45]
	v_mfma_f32_16x16x32_bf16 v[42:45], v[170:173], v[206:209], v[42:45]
	v_mfma_f32_16x16x32_bf16 v[30:33], v[152:155], v[210:213], v[30:33]
	v_mfma_f32_16x16x32_bf16 v[30:33], v[162:165], v[214:217], v[30:33]
	v_mfma_f32_16x16x32_bf16 v[26:29], v[166:169], v[210:213], v[26:29]
	v_mfma_f32_16x16x32_bf16 v[26:29], v[170:173], v[214:217], v[26:29]
	v_mfma_f32_16x16x32_bf16 v[14:17], v[152:155], v[218:221], v[14:17]
	v_mfma_f32_16x16x32_bf16 v[14:17], v[162:165], v[222:225], v[14:17]
	v_mfma_f32_16x16x32_bf16 v[10:13], v[166:169], v[218:221], v[10:13]
	v_mfma_f32_16x16x32_bf16 v[10:13], v[170:173], v[222:225], v[10:13]
	v_mfma_f32_16x16x32_bf16 v[54:57], v[174:177], v[194:197], v[54:57]
	v_mfma_f32_16x16x32_bf16 v[54:57], v[182:185], v[198:201], v[54:57]
	v_mfma_f32_16x16x32_bf16 v[50:53], v[186:189], v[194:197], v[50:53]
	v_mfma_f32_16x16x32_bf16 v[50:53], v[190:193], v[198:201], v[50:53]
	v_mfma_f32_16x16x32_bf16 v[38:41], v[174:177], v[202:205], v[38:41]
	v_mfma_f32_16x16x32_bf16 v[38:41], v[182:185], v[206:209], v[38:41]
	v_mfma_f32_16x16x32_bf16 v[34:37], v[186:189], v[202:205], v[34:37]
	v_mfma_f32_16x16x32_bf16 v[34:37], v[190:193], v[206:209], v[34:37]
	v_mfma_f32_16x16x32_bf16 v[22:25], v[174:177], v[210:213], v[22:25]
	v_mfma_f32_16x16x32_bf16 v[22:25], v[182:185], v[214:217], v[22:25]
	v_mfma_f32_16x16x32_bf16 v[18:21], v[186:189], v[210:213], v[18:21]
	v_mfma_f32_16x16x32_bf16 v[18:21], v[190:193], v[214:217], v[18:21]
	v_mfma_f32_16x16x32_bf16 v[6:9], v[174:177], v[218:221], v[6:9]
	v_mfma_f32_16x16x32_bf16 v[6:9], v[182:185], v[222:225], v[6:9]
	v_mfma_f32_16x16x32_bf16 v[2:5], v[186:189], v[218:221], v[2:5]
	v_mfma_f32_16x16x32_bf16 v[2:5], v[190:193], v[222:225], v[2:5]
	s_barrier
	s_add_u32 s100, s16, 0x100000
	s_addc_u32 s101, s17, 0
	s_mov_b32 m0, s29
	ds_read_b128 v[152:155], v252 offset:32768
	ds_read_b128 v[162:165], v252 offset:33792
	global_load_lds_dwordx4 v146, s[100:101]
	s_mov_b32 m0, s36
	ds_read_b128 v[166:169], v252 offset:34816
	ds_read_b128 v[170:173], v252 offset:35840
	global_load_lds_dwordx4 v142, s[100:101]
	ds_read_b128 v[174:177], v252 offset:49152
	ds_read_b128 v[182:185], v252 offset:50176
	ds_read_b128 v[186:189], v252 offset:51200
	ds_read_b128 v[190:193], v252 offset:52224
	ds_read_b128 v[194:197], v161 offset:32768
	ds_read_b128 v[198:201], v161 offset:33792
	ds_read_b128 v[202:205], v161 offset:34816
	ds_read_b128 v[206:209], v161 offset:35840
	ds_read_b128 v[210:213], v161 offset:36864
	ds_read_b128 v[214:217], v161 offset:37888
	ds_read_b128 v[218:221], v161 offset:38912
	ds_read_b128 v[222:225], v161 offset:39936
	s_waitcnt vmcnt(9)
	s_waitcnt lgkmcnt(0)
	s_barrier
	v_mfma_f32_16x16x32_bf16 v[126:129], v[152:155], v[194:197], v[126:129]
	v_mfma_f32_16x16x32_bf16 v[126:129], v[162:165], v[198:201], v[126:129]
	v_mfma_f32_16x16x32_bf16 v[122:125], v[166:169], v[194:197], v[122:125]
	v_mfma_f32_16x16x32_bf16 v[122:125], v[170:173], v[198:201], v[122:125]
	v_mfma_f32_16x16x32_bf16 v[110:113], v[152:155], v[202:205], v[110:113]
	v_mfma_f32_16x16x32_bf16 v[110:113], v[162:165], v[206:209], v[110:113]
	v_mfma_f32_16x16x32_bf16 v[106:109], v[166:169], v[202:205], v[106:109]
	v_mfma_f32_16x16x32_bf16 v[106:109], v[170:173], v[206:209], v[106:109]
	v_mfma_f32_16x16x32_bf16 v[94:97], v[152:155], v[210:213], v[94:97]
	v_mfma_f32_16x16x32_bf16 v[94:97], v[162:165], v[214:217], v[94:97]
	v_mfma_f32_16x16x32_bf16 v[90:93], v[166:169], v[210:213], v[90:93]
	v_mfma_f32_16x16x32_bf16 v[90:93], v[170:173], v[214:217], v[90:93]
	v_mfma_f32_16x16x32_bf16 v[78:81], v[152:155], v[218:221], v[78:81]
	v_mfma_f32_16x16x32_bf16 v[78:81], v[162:165], v[222:225], v[78:81]
	v_mfma_f32_16x16x32_bf16 v[74:77], v[166:169], v[218:221], v[74:77]
	v_mfma_f32_16x16x32_bf16 v[74:77], v[170:173], v[222:225], v[74:77]
	v_mfma_f32_16x16x32_bf16 v[118:121], v[174:177], v[194:197], v[118:121]
	v_mfma_f32_16x16x32_bf16 v[118:121], v[182:185], v[198:201], v[118:121]
	v_mfma_f32_16x16x32_bf16 v[114:117], v[186:189], v[194:197], v[114:117]
	v_mfma_f32_16x16x32_bf16 v[114:117], v[190:193], v[198:201], v[114:117]
	v_mfma_f32_16x16x32_bf16 v[102:105], v[174:177], v[202:205], v[102:105]
	v_mfma_f32_16x16x32_bf16 v[102:105], v[182:185], v[206:209], v[102:105]
	v_mfma_f32_16x16x32_bf16 v[98:101], v[186:189], v[202:205], v[98:101]
	v_mfma_f32_16x16x32_bf16 v[98:101], v[190:193], v[206:209], v[98:101]
	v_mfma_f32_16x16x32_bf16 v[86:89], v[174:177], v[210:213], v[86:89]
	v_mfma_f32_16x16x32_bf16 v[86:89], v[182:185], v[214:217], v[86:89]
	v_mfma_f32_16x16x32_bf16 v[82:85], v[186:189], v[210:213], v[82:85]
	v_mfma_f32_16x16x32_bf16 v[82:85], v[190:193], v[214:217], v[82:85]
	v_mfma_f32_16x16x32_bf16 v[70:73], v[174:177], v[218:221], v[70:73]
	v_mfma_f32_16x16x32_bf16 v[70:73], v[182:185], v[222:225], v[70:73]
	v_mfma_f32_16x16x32_bf16 v[66:69], v[186:189], v[218:221], v[66:69]
	v_mfma_f32_16x16x32_bf16 v[66:69], v[190:193], v[222:225], v[66:69]
	s_barrier
	s_add_u32 s14, s14, 0x80
	s_addc_u32 s15, s15, 0
	s_add_i32 m0, s28, 0x18000
	ds_read_b128 v[194:197], v161 offset:49152
	ds_read_b128 v[198:201], v161 offset:50176
	global_load_lds_dwordx4 v144, s[14:15]
	s_add_i32 m0, s28, 0x1a000
	s_add_u32 s98, s98, 0x80
	s_addc_u32 s99, s99, 0
	ds_read_b128 v[202:205], v161 offset:51200
	global_load_lds_dwordx4 v140, s[14:15]
	s_add_i32 m0, s28, 0x1c000
	ds_read_b128 v[206:209], v161 offset:52224
	ds_read_b128 v[210:213], v161 offset:53248
	global_load_lds_dwordx4 v144, s[98:99]
	s_add_i32 m0, s28, 0x1e000
	s_add_u32 s16, s16, 0x80
	s_addc_u32 s17, s17, 0
	ds_read_b128 v[214:217], v161 offset:54272
	ds_read_b128 v[218:221], v161 offset:55296
	global_load_lds_dwordx4 v140, s[98:99]
	s_mov_b32 m0, s45
	ds_read_b128 v[222:225], v161 offset:56320
	global_load_lds_dwordx4 v146, s[16:17]
	s_mov_b32 m0, s46
	s_nop 0
	global_load_lds_dwordx4 v142, s[16:17]
	s_waitcnt vmcnt(8)
	s_waitcnt lgkmcnt(0)
	s_barrier
	v_mfma_f32_16x16x32_bf16 v[62:65], v[152:155], v[194:197], v[62:65]
	v_mfma_f32_16x16x32_bf16 v[62:65], v[162:165], v[198:201], v[62:65]
	v_mfma_f32_16x16x32_bf16 v[58:61], v[166:169], v[194:197], v[58:61]
	v_mfma_f32_16x16x32_bf16 v[58:61], v[170:173], v[198:201], v[58:61]
	v_mfma_f32_16x16x32_bf16 v[46:49], v[152:155], v[202:205], v[46:49]
	v_mfma_f32_16x16x32_bf16 v[46:49], v[162:165], v[206:209], v[46:49]
	v_mfma_f32_16x16x32_bf16 v[42:45], v[166:169], v[202:205], v[42:45]
	v_mfma_f32_16x16x32_bf16 v[42:45], v[170:173], v[206:209], v[42:45]
	v_mfma_f32_16x16x32_bf16 v[30:33], v[152:155], v[210:213], v[30:33]
	v_mfma_f32_16x16x32_bf16 v[30:33], v[162:165], v[214:217], v[30:33]
	v_mfma_f32_16x16x32_bf16 v[26:29], v[166:169], v[210:213], v[26:29]
	v_mfma_f32_16x16x32_bf16 v[26:29], v[170:173], v[214:217], v[26:29]
	v_mfma_f32_16x16x32_bf16 v[14:17], v[152:155], v[218:221], v[14:17]
	v_mfma_f32_16x16x32_bf16 v[14:17], v[162:165], v[222:225], v[14:17]
	v_mfma_f32_16x16x32_bf16 v[10:13], v[166:169], v[218:221], v[10:13]
	v_mfma_f32_16x16x32_bf16 v[10:13], v[170:173], v[222:225], v[10:13]
	v_mfma_f32_16x16x32_bf16 v[54:57], v[174:177], v[194:197], v[54:57]
	v_mfma_f32_16x16x32_bf16 v[54:57], v[182:185], v[198:201], v[54:57]
	v_mfma_f32_16x16x32_bf16 v[50:53], v[186:189], v[194:197], v[50:53]
	v_mfma_f32_16x16x32_bf16 v[50:53], v[190:193], v[198:201], v[50:53]
	v_mfma_f32_16x16x32_bf16 v[38:41], v[174:177], v[202:205], v[38:41]
	v_mfma_f32_16x16x32_bf16 v[38:41], v[182:185], v[206:209], v[38:41]
	v_mfma_f32_16x16x32_bf16 v[34:37], v[186:189], v[202:205], v[34:37]
	v_mfma_f32_16x16x32_bf16 v[34:37], v[190:193], v[206:209], v[34:37]
	v_mfma_f32_16x16x32_bf16 v[22:25], v[174:177], v[210:213], v[22:25]
	v_mfma_f32_16x16x32_bf16 v[22:25], v[182:185], v[214:217], v[22:25]
	v_mfma_f32_16x16x32_bf16 v[18:21], v[186:189], v[210:213], v[18:21]
	v_mfma_f32_16x16x32_bf16 v[18:21], v[190:193], v[214:217], v[18:21]
	v_mfma_f32_16x16x32_bf16 v[6:9], v[174:177], v[218:221], v[6:9]
	v_mfma_f32_16x16x32_bf16 v[6:9], v[182:185], v[222:225], v[6:9]
	v_mfma_f32_16x16x32_bf16 v[2:5], v[186:189], v[218:221], v[2:5]
	v_mfma_f32_16x16x32_bf16 v[2:5], v[190:193], v[222:225], v[2:5]
	s_barrier
	s_add_i32 s39, s39, 2
	s_add_u32 s12, s12, 0x100
	s_addc_u32 s13, s13, 0
	s_add_u32 s0, s0, 0x100
	s_addc_u32 s1, s1, 0
	s_cmp_gt_u32 s39, 61
	s_cbranch_scc0 .LBB0_341
	s_and_b64 vcc, exec, s[34:35]
	s_cbranch_vccz .LBB0_344
	s_barrier

.LBB0_571:
	s_and_b32 s98, s47, 3
	s_and_b32 s99, s46, 7
	s_lshl_b32 s98, s98, 6
	s_lshl_b32 s99, s99, 5
	v_and_b32_e32 v244, 63, v0
	v_mul_u32_u24_e32 v245, 43, v244
	v_lshrrev_b32_e32 v245, 10, v245
	v_mul_u32_u24_e32 v245, 24, v245
	v_sub_u32_e32 v244, v244, v245
	v_lshrrev_b32_e32 v245, 6, v0
	v_mad_u32_u24 v244, v245, 24, v244
	v_cmp_gt_u32_e32 vcc, 0x80, v244
	v_and_b32_e32 v245, 63, v244
	v_add_u32_e32 v245, s98, v245
	v_lshrrev_b32_e32 v246, 6, v244
	v_subrev_u32_e32 v247, 0x80, v244
	v_and_b32_e32 v248, 31, v247
	v_add_u32_e32 v248, s99, v248
	v_lshrrev_b32_e32 v247, 5, v247
	v_cndmask_b32_e32 v245, v248, v245, vcc
	v_cndmask_b32_e32 v246, v247, v246, vcc
	v_lshlrev_b32_e32 v245, 13, v245
	v_lshl_add_u32 v245, v246, 7, v245
	v_add_u32_e32 v244, 0x80, v245
	v_mov_b32_e32 v245, 0
	v_mov_b32_e32 v246, s12
	v_mov_b32_e32 v247, s13
	v_mov_b32_e32 v248, s14
	v_mov_b32_e32 v249, s15
	v_cndmask_b32_e32 v246, v248, v246, vcc
	v_cndmask_b32_e32 v247, v249, v247, vcc
	v_lshl_add_u64 v[242:243], v[246:247], 0, v[244:245]
	v_add_u32_e32 v252, 0x10000, v159
	s_add_u32 s12, s12, 0x100080
	s_addc_u32 s13, s13, 0
	s_add_u32 s0, s14, 0x100
	v_mov_b32_e32 v2, 0
	s_addc_u32 s1, s15, 0
	s_mov_b32 s35, -2
	v_mov_b32_e32 v3, v2
	v_mov_b32_e32 v4, v2
	v_mov_b32_e32 v5, v2
	v_mov_b32_e32 v6, v2
	v_mov_b32_e32 v7, v2
	v_mov_b32_e32 v8, v2
	v_mov_b32_e32 v9, v2
	v_mov_b32_e32 v18, v2
	v_mov_b32_e32 v19, v2
	v_mov_b32_e32 v20, v2
	v_mov_b32_e32 v21, v2
	v_mov_b32_e32 v22, v2
	v_mov_b32_e32 v23, v2
	v_mov_b32_e32 v24, v2
	v_mov_b32_e32 v25, v2
	v_mov_b32_e32 v34, v2
	v_mov_b32_e32 v35, v2
	v_mov_b32_e32 v36, v2
	v_mov_b32_e32 v37, v2
	v_mov_b32_e32 v38, v2
	v_mov_b32_e32 v39, v2
	v_mov_b32_e32 v40, v2
	v_mov_b32_e32 v41, v2
	v_mov_b32_e32 v50, v2
	v_mov_b32_e32 v51, v2
	v_mov_b32_e32 v52, v2
	v_mov_b32_e32 v53, v2
	v_mov_b32_e32 v54, v2
	v_mov_b32_e32 v55, v2
	v_mov_b32_e32 v56, v2
	v_mov_b32_e32 v57, v2
	v_mov_b32_e32 v10, v2
	v_mov_b32_e32 v11, v2
	v_mov_b32_e32 v12, v2
	v_mov_b32_e32 v13, v2
	v_mov_b32_e32 v14, v2
	v_mov_b32_e32 v15, v2
	v_mov_b32_e32 v16, v2
	v_mov_b32_e32 v17, v2
	v_mov_b32_e32 v26, v2
	v_mov_b32_e32 v27, v2
	v_mov_b32_e32 v28, v2
	v_mov_b32_e32 v29, v2
	v_mov_b32_e32 v30, v2
	v_mov_b32_e32 v31, v2
	v_mov_b32_e32 v32, v2
	v_mov_b32_e32 v33, v2
	v_mov_b32_e32 v42, v2
	v_mov_b32_e32 v43, v2
	v_mov_b32_e32 v44, v2
	v_mov_b32_e32 v45, v2
	v_mov_b32_e32 v46, v2
	v_mov_b32_e32 v47, v2
	v_mov_b32_e32 v48, v2
	v_mov_b32_e32 v49, v2
	v_mov_b32_e32 v58, v2
	v_mov_b32_e32 v59, v2
	v_mov_b32_e32 v60, v2
	v_mov_b32_e32 v61, v2
	v_mov_b32_e32 v62, v2
	v_mov_b32_e32 v63, v2
	v_mov_b32_e32 v64, v2
	v_mov_b32_e32 v65, v2
	v_mov_b32_e32 v66, v2
	v_mov_b32_e32 v67, v2
	v_mov_b32_e32 v68, v2
	v_mov_b32_e32 v69, v2
	v_mov_b32_e32 v70, v2
	v_mov_b32_e32 v71, v2
	v_mov_b32_e32 v72, v2
	v_mov_b32_e32 v73, v2
	v_mov_b32_e32 v82, v2
	v_mov_b32_e32 v83, v2
	v_mov_b32_e32 v84, v2
	v_mov_b32_e32 v85, v2
	v_mov_b32_e32 v86, v2
	v_mov_b32_e32 v87, v2
	v_mov_b32_e32 v88, v2
	v_mov_b32_e32 v89, v2
	v_mov_b32_e32 v98, v2
	v_mov_b32_e32 v99, v2
	v_mov_b32_e32 v100, v2
	v_mov_b32_e32 v101, v2
	v_mov_b32_e32 v102, v2
	v_mov_b32_e32 v103, v2
	v_mov_b32_e32 v104, v2
	v_mov_b32_e32 v105, v2
	v_mov_b32_e32 v114, v2
	v_mov_b32_e32 v115, v2
	v_mov_b32_e32 v116, v2
	v_mov_b32_e32 v117, v2
	v_mov_b32_e32 v118, v2
	v_mov_b32_e32 v119, v2
	v_mov_b32_e32 v120, v2
	v_mov_b32_e32 v121, v2
	v_mov_b32_e32 v74, v2
	v_mov_b32_e32 v75, v2
	v_mov_b32_e32 v76, v2
	v_mov_b32_e32 v77, v2
	v_mov_b32_e32 v78, v2
	v_mov_b32_e32 v79, v2
	v_mov_b32_e32 v80, v2
	v_mov_b32_e32 v81, v2
	v_mov_b32_e32 v90, v2
	v_mov_b32_e32 v91, v2
	v_mov_b32_e32 v92, v2
	v_mov_b32_e32 v93, v2
	v_mov_b32_e32 v94, v2
	v_mov_b32_e32 v95, v2
	v_mov_b32_e32 v96, v2
	v_mov_b32_e32 v97, v2
	v_mov_b32_e32 v106, v2
	v_mov_b32_e32 v107, v2
	v_mov_b32_e32 v108, v2
	v_mov_b32_e32 v109, v2
	v_mov_b32_e32 v110, v2
	v_mov_b32_e32 v111, v2
	v_mov_b32_e32 v112, v2
	v_mov_b32_e32 v113, v2
	v_mov_b32_e32 v122, v2
	v_mov_b32_e32 v123, v2
	v_mov_b32_e32 v124, v2
	v_mov_b32_e32 v125, v2
	v_mov_b32_e32 v126, v2
	v_mov_b32_e32 v127, v2
	v_mov_b32_e32 v128, v2
	v_mov_b32_e32 v129, v2
.LBB0_572:
	s_add_u32 s14, s12, 0xfff00080
	s_addc_u32 s15, s13, -1
	s_cmp_eq_u32 s35, 60
	s_cselect_b32 s17, s51, s15
	s_cselect_b32 s16, s50, s14
	s_cselect_b32 s15, s53, s1
	s_cselect_b32 s14, s52, s0
	s_cmp_lt_i32 s35, 57
	s_cselect_b32 s100, 0x100, 0
	s_mov_b32 s101, 0
	v_lshl_add_u64 v[242:243], v[242:243], 0, s[100:101]
	s_add_i32 m0, s8, 0xc000
	ds_read_b128 v[152:155], v252
	ds_read_b128 v[162:165], v252 offset:1024
	global_load_lds_dwordx4 v148, s[12:13]
	s_add_i32 m0, s8, 0xe000
	ds_read_b128 v[166:169], v252 offset:2048
	ds_read_b128 v[170:173], v252 offset:3072
	global_load_lds_dwordx4 v150, s[12:13]
	ds_read_b128 v[174:177], v252 offset:16384
	ds_read_b128 v[182:185], v252 offset:17408
	ds_read_b128 v[186:189], v252 offset:18432
	ds_read_b128 v[190:193], v252 offset:19456
	ds_read_b128 v[194:197], v161
	ds_read_b128 v[198:201], v161 offset:1024
	ds_read_b128 v[202:205], v161 offset:2048
	ds_read_b128 v[206:209], v161 offset:3072
	ds_read_b128 v[210:213], v161 offset:4096
	ds_read_b128 v[214:217], v161 offset:5120
	ds_read_b128 v[218:221], v161 offset:6144
	ds_read_b128 v[222:225], v161 offset:7168
	s_waitcnt vmcnt(8)
	s_mov_b32 m0, 0x21800
	s_mov_b64 exec, 0xffffff
	s_waitcnt lgkmcnt(0)
	global_load_lds_dword v[242:243], off
	s_mov_b64 exec, -1
	s_barrier
	v_mfma_f32_16x16x32_bf16 v[126:129], v[152:155], v[194:197], v[126:129]
	v_mfma_f32_16x16x32_bf16 v[126:129], v[162:165], v[198:201], v[126:129]
	v_mfma_f32_16x16x32_bf16 v[122:125], v[166:169], v[194:197], v[122:125]
	v_mfma_f32_16x16x32_bf16 v[122:125], v[170:173], v[198:201], v[122:125]
	v_mfma_f32_16x16x32_bf16 v[110:113], v[152:155], v[202:205], v[110:113]
	v_mfma_f32_16x16x32_bf16 v[110:113], v[162:165], v[206:209], v[110:113]
	v_mfma_f32_16x16x32_bf16 v[106:109], v[166:169], v[202:205], v[106:109]
	v_mfma_f32_16x16x32_bf16 v[106:109], v[170:173], v[206:209], v[106:109]
	v_mfma_f32_16x16x32_bf16 v[94:97], v[152:155], v[210:213], v[94:97]
	v_mfma_f32_16x16x32_bf16 v[94:97], v[162:165], v[214:217], v[94:97]
	v_mfma_f32_16x16x32_bf16 v[90:93], v[166:169], v[210:213], v[90:93]
	v_mfma_f32_16x16x32_bf16 v[90:93], v[170:173], v[214:217], v[90:93]
	v_mfma_f32_16x16x32_bf16 v[78:81], v[152:155], v[218:221], v[78:81]
	v_mfma_f32_16x16x32_bf16 v[78:81], v[162:165], v[222:225], v[78:81]
	v_mfma_f32_16x16x32_bf16 v[74:77], v[166:169], v[218:221], v[74:77]
	v_mfma_f32_16x16x32_bf16 v[74:77], v[170:173], v[222:225], v[74:77]
	v_mfma_f32_16x16x32_bf16 v[118:121], v[174:177], v[194:197], v[118:121]
	v_mfma_f32_16x16x32_bf16 v[118:121], v[182:185], v[198:201], v[118:121]
	v_mfma_f32_16x16x32_bf16 v[114:117], v[186:189], v[194:197], v[114:117]
	v_mfma_f32_16x16x32_bf16 v[114:117], v[190:193], v[198:201], v[114:117]
	v_mfma_f32_16x16x32_bf16 v[102:105], v[174:177], v[202:205], v[102:105]
	v_mfma_f32_16x16x32_bf16 v[102:105], v[182:185], v[206:209], v[102:105]
	v_mfma_f32_16x16x32_bf16 v[98:101], v[186:189], v[202:205], v[98:101]
	v_mfma_f32_16x16x32_bf16 v[98:101], v[190:193], v[206:209], v[98:101]
	v_mfma_f32_16x16x32_bf16 v[86:89], v[174:177], v[210:213], v[86:89]
	v_mfma_f32_16x16x32_bf16 v[86:89], v[182:185], v[214:217], v[86:89]
	v_mfma_f32_16x16x32_bf16 v[82:85], v[186:189], v[210:213], v[82:85]
	v_mfma_f32_16x16x32_bf16 v[82:85], v[190:193], v[214:217], v[82:85]
	v_mfma_f32_16x16x32_bf16 v[70:73], v[174:177], v[218:221], v[70:73]
	v_mfma_f32_16x16x32_bf16 v[70:73], v[182:185], v[222:225], v[70:73]
	v_mfma_f32_16x16x32_bf16 v[66:69], v[186:189], v[218:221], v[66:69]
	v_mfma_f32_16x16x32_bf16 v[66:69], v[190:193], v[222:225], v[66:69]
	s_barrier
	s_add_i32 m0, s28, 0x10000
	ds_read_b128 v[194:197], v161 offset:16384
	ds_read_b128 v[198:201], v161 offset:17408
	global_load_lds_dwordx4 v144, s[14:15]
	s_add_i32 m0, s28, 0x12000
	s_add_u32 s98, s14, 0x100000
	s_addc_u32 s99, s15, 0
	ds_read_b128 v[202:205], v161 offset:18432
	global_load_lds_dwordx4 v140, s[14:15]
	s_add_i32 m0, s28, 0x14000
	ds_read_b128 v[206:209], v161 offset:19456
	ds_read_b128 v[210:213], v161 offset:20480
	global_load_lds_dwordx4 v144, s[98:99]
	s_add_i32 m0, s28, 0x16000
	ds_read_b128 v[214:217], v161 offset:21504
	ds_read_b128 v[218:221], v161 offset:22528
	global_load_lds_dwordx4 v140, s[98:99]
	s_mov_b32 m0, s8
	ds_read_b128 v[222:225], v161 offset:23552
	global_load_lds_dwordx4 v146, s[16:17]
	s_mov_b32 m0, s9
	s_nop 0
	global_load_lds_dwordx4 v142, s[16:17]
	s_waitcnt vmcnt(9)
	s_waitcnt lgkmcnt(0)
	s_barrier
	v_mfma_f32_16x16x32_bf16 v[62:65], v[152:155], v[194:197], v[62:65]
	v_mfma_f32_16x16x32_bf16 v[62:65], v[162:165], v[198:201], v[62:65]
	v_mfma_f32_16x16x32_bf16 v[58:61], v[166:169], v[194:197], v[58:61]
	v_mfma_f32_16x16x32_bf16 v[58:61], v[170:173], v[198:201], v[58:61]
	v_mfma_f32_16x16x32_bf16 v[46:49], v[152:155], v[202:205], v[46:49]
	v_mfma_f32_16x16x32_bf16 v[46:49], v[162:165], v[206:209], v[46:49]
	v_mfma_f32_16x16x32_bf16 v[42:45], v[166:169], v[202:205], v[42:45]
	v_mfma_f32_16x16x32_bf16 v[42:45], v[170:173], v[206:209], v[42:45]
	v_mfma_f32_16x16x32_bf16 v[30:33], v[152:155], v[210:213], v[30:33]
	v_mfma_f32_16x16x32_bf16 v[30:33], v[162:165], v[214:217], v[30:33]
	v_mfma_f32_16x16x32_bf16 v[26:29], v[166:169], v[210:213], v[26:29]
	v_mfma_f32_16x16x32_bf16 v[26:29], v[170:173], v[214:217], v[26:29]
	v_mfma_f32_16x16x32_bf16 v[14:17], v[152:155], v[218:221], v[14:17]
	v_mfma_f32_16x16x32_bf16 v[14:17], v[162:165], v[222:225], v[14:17]
	v_mfma_f32_16x16x32_bf16 v[10:13], v[166:169], v[218:221], v[10:13]
	v_mfma_f32_16x16x32_bf16 v[10:13], v[170:173], v[222:225], v[10:13]
	v_mfma_f32_16x16x32_bf16 v[54:57], v[174:177], v[194:197], v[54:57]
	v_mfma_f32_16x16x32_bf16 v[54:57], v[182:185], v[198:201], v[54:57]
	v_mfma_f32_16x16x32_bf16 v[50:53], v[186:189], v[194:197], v[50:53]
	v_mfma_f32_16x16x32_bf16 v[50:53], v[190:193], v[198:201], v[50:53]
	v_mfma_f32_16x16x32_bf16 v[38:41], v[174:177], v[202:205], v[38:41]
	v_mfma_f32_16x16x32_bf16 v[38:41], v[182:185], v[206:209], v[38:41]
	v_mfma_f32_16x16x32_bf16 v[34:37], v[186:189], v[202:205], v[34:37]
	v_mfma_f32_16x16x32_bf16 v[34:37], v[190:193], v[206:209], v[34:37]
	v_mfma_f32_16x16x32_bf16 v[22:25], v[174:177], v[210:213], v[22:25]
	v_mfma_f32_16x16x32_bf16 v[22:25], v[182:185], v[214:217], v[22:25]
	v_mfma_f32_16x16x32_bf16 v[18:21], v[186:189], v[210:213], v[18:21]
	v_mfma_f32_16x16x32_bf16 v[18:21], v[190:193], v[214:217], v[18:21]
	v_mfma_f32_16x16x32_bf16 v[6:9], v[174:177], v[218:221], v[6:9]
	v_mfma_f32_16x16x32_bf16 v[6:9], v[182:185], v[222:225], v[6:9]
	v_mfma_f32_16x16x32_bf16 v[2:5], v[186:189], v[218:221], v[2:5]
	v_mfma_f32_16x16x32_bf16 v[2:5], v[190:193], v[222:225], v[2:5]
	s_barrier
	s_add_u32 s100, s16, 0x100000
	s_addc_u32 s101, s17, 0
	s_mov_b32 m0, s29
	ds_read_b128 v[152:155], v252 offset:32768
	ds_read_b128 v[162:165], v252 offset:33792
	global_load_lds_dwordx4 v146, s[100:101]
	s_mov_b32 m0, s36
	ds_read_b128 v[166:169], v252 offset:34816
	ds_read_b128 v[170:173], v252 offset:35840
	global_load_lds_dwordx4 v142, s[100:101]
	ds_read_b128 v[174:177], v252 offset:49152
	ds_read_b128 v[182:185], v252 offset:50176
	ds_read_b128 v[186:189], v252 offset:51200
	ds_read_b128 v[190:193], v252 offset:52224
	ds_read_b128 v[194:197], v161 offset:32768
	ds_read_b128 v[198:201], v161 offset:33792
	ds_read_b128 v[202:205], v161 offset:34816
	ds_read_b128 v[206:209], v161 offset:35840
	ds_read_b128 v[210:213], v161 offset:36864
	ds_read_b128 v[214:217], v161 offset:37888
	ds_read_b128 v[218:221], v161 offset:38912
	ds_read_b128 v[222:225], v161 offset:39936
	s_waitcnt vmcnt(9)
	s_waitcnt lgkmcnt(0)
	s_barrier
	v_mfma_f32_16x16x32_bf16 v[126:129], v[152:155], v[194:197], v[126:129]
	v_mfma_f32_16x16x32_bf16 v[126:129], v[162:165], v[198:201], v[126:129]
	v_mfma_f32_16x16x32_bf16 v[122:125], v[166:169], v[194:197], v[122:125]
	v_mfma_f32_16x16x32_bf16 v[122:125], v[170:173], v[198:201], v[122:125]
	v_mfma_f32_16x16x32_bf16 v[110:113], v[152:155], v[202:205], v[110:113]
	v_mfma_f32_16x16x32_bf16 v[110:113], v[162:165], v[206:209], v[110:113]
	v_mfma_f32_16x16x32_bf16 v[106:109], v[166:169], v[202:205], v[106:109]
	v_mfma_f32_16x16x32_bf16 v[106:109], v[170:173], v[206:209], v[106:109]
	v_mfma_f32_16x16x32_bf16 v[94:97], v[152:155], v[210:213], v[94:97]
	v_mfma_f32_16x16x32_bf16 v[94:97], v[162:165], v[214:217], v[94:97]
	v_mfma_f32_16x16x32_bf16 v[90:93], v[166:169], v[210:213], v[90:93]
	v_mfma_f32_16x16x32_bf16 v[90:93], v[170:173], v[214:217], v[90:93]
	v_mfma_f32_16x16x32_bf16 v[78:81], v[152:155], v[218:221], v[78:81]
	v_mfma_f32_16x16x32_bf16 v[78:81], v[162:165], v[222:225], v[78:81]
	v_mfma_f32_16x16x32_bf16 v[74:77], v[166:169], v[218:221], v[74:77]
	v_mfma_f32_16x16x32_bf16 v[74:77], v[170:173], v[222:225], v[74:77]
	v_mfma_f32_16x16x32_bf16 v[118:121], v[174:177], v[194:197], v[118:121]
	v_mfma_f32_16x16x32_bf16 v[118:121], v[182:185], v[198:201], v[118:121]
	v_mfma_f32_16x16x32_bf16 v[114:117], v[186:189], v[194:197], v[114:117]
	v_mfma_f32_16x16x32_bf16 v[114:117], v[190:193], v[198:201], v[114:117]
	v_mfma_f32_16x16x32_bf16 v[102:105], v[174:177], v[202:205], v[102:105]
	v_mfma_f32_16x16x32_bf16 v[102:105], v[182:185], v[206:209], v[102:105]
	v_mfma_f32_16x16x32_bf16 v[98:101], v[186:189], v[202:205], v[98:101]
	v_mfma_f32_16x16x32_bf16 v[98:101], v[190:193], v[206:209], v[98:101]
	v_mfma_f32_16x16x32_bf16 v[86:89], v[174:177], v[210:213], v[86:89]
	v_mfma_f32_16x16x32_bf16 v[86:89], v[182:185], v[214:217], v[86:89]
	v_mfma_f32_16x16x32_bf16 v[82:85], v[186:189], v[210:213], v[82:85]
	v_mfma_f32_16x16x32_bf16 v[82:85], v[190:193], v[214:217], v[82:85]
	v_mfma_f32_16x16x32_bf16 v[70:73], v[174:177], v[218:221], v[70:73]
	v_mfma_f32_16x16x32_bf16 v[70:73], v[182:185], v[222:225], v[70:73]
	v_mfma_f32_16x16x32_bf16 v[66:69], v[186:189], v[218:221], v[66:69]
	v_mfma_f32_16x16x32_bf16 v[66:69], v[190:193], v[222:225], v[66:69]
	s_barrier
	s_add_u32 s14, s14, 0x80
	s_addc_u32 s15, s15, 0
	s_add_i32 m0, s28, 0x18000
	ds_read_b128 v[194:197], v161 offset:49152
	ds_read_b128 v[198:201], v161 offset:50176
	global_load_lds_dwordx4 v144, s[14:15]
	s_add_i32 m0, s28, 0x1a000
	s_add_u32 s98, s98, 0x80
	s_addc_u32 s99, s99, 0
	ds_read_b128 v[202:205], v161 offset:51200
	global_load_lds_dwordx4 v140, s[14:15]
	s_add_i32 m0, s28, 0x1c000
	ds_read_b128 v[206:209], v161 offset:52224
	ds_read_b128 v[210:213], v161 offset:53248
	global_load_lds_dwordx4 v144, s[98:99]
	s_add_i32 m0, s28, 0x1e000
	s_add_u32 s16, s16, 0x80
	s_addc_u32 s17, s17, 0
	ds_read_b128 v[214:217], v161 offset:54272
	ds_read_b128 v[218:221], v161 offset:55296
	global_load_lds_dwordx4 v140, s[98:99]
	s_mov_b32 m0, s39
	ds_read_b128 v[222:225], v161 offset:56320
	global_load_lds_dwordx4 v146, s[16:17]
	s_mov_b32 m0, s44
	s_nop 0
	global_load_lds_dwordx4 v142, s[16:17]
	s_waitcnt vmcnt(8)
	s_waitcnt lgkmcnt(0)
	s_barrier
	v_mfma_f32_16x16x32_bf16 v[62:65], v[152:155], v[194:197], v[62:65]
	v_mfma_f32_16x16x32_bf16 v[62:65], v[162:165], v[198:201], v[62:65]
	v_mfma_f32_16x16x32_bf16 v[58:61], v[166:169], v[194:197], v[58:61]
	v_mfma_f32_16x16x32_bf16 v[58:61], v[170:173], v[198:201], v[58:61]
	v_mfma_f32_16x16x32_bf16 v[46:49], v[152:155], v[202:205], v[46:49]
	v_mfma_f32_16x16x32_bf16 v[46:49], v[162:165], v[206:209], v[46:49]
	v_mfma_f32_16x16x32_bf16 v[42:45], v[166:169], v[202:205], v[42:45]
	v_mfma_f32_16x16x32_bf16 v[42:45], v[170:173], v[206:209], v[42:45]
	v_mfma_f32_16x16x32_bf16 v[30:33], v[152:155], v[210:213], v[30:33]
	v_mfma_f32_16x16x32_bf16 v[30:33], v[162:165], v[214:217], v[30:33]
	v_mfma_f32_16x16x32_bf16 v[26:29], v[166:169], v[210:213], v[26:29]
	v_mfma_f32_16x16x32_bf16 v[26:29], v[170:173], v[214:217], v[26:29]
	v_mfma_f32_16x16x32_bf16 v[14:17], v[152:155], v[218:221], v[14:17]
	v_mfma_f32_16x16x32_bf16 v[14:17], v[162:165], v[222:225], v[14:17]
	v_mfma_f32_16x16x32_bf16 v[10:13], v[166:169], v[218:221], v[10:13]
	v_mfma_f32_16x16x32_bf16 v[10:13], v[170:173], v[222:225], v[10:13]
	v_mfma_f32_16x16x32_bf16 v[54:57], v[174:177], v[194:197], v[54:57]
	v_mfma_f32_16x16x32_bf16 v[54:57], v[182:185], v[198:201], v[54:57]
	v_mfma_f32_16x16x32_bf16 v[50:53], v[186:189], v[194:197], v[50:53]
	v_mfma_f32_16x16x32_bf16 v[50:53], v[190:193], v[198:201], v[50:53]
	v_mfma_f32_16x16x32_bf16 v[38:41], v[174:177], v[202:205], v[38:41]
	v_mfma_f32_16x16x32_bf16 v[38:41], v[182:185], v[206:209], v[38:41]
	v_mfma_f32_16x16x32_bf16 v[34:37], v[186:189], v[202:205], v[34:37]
	v_mfma_f32_16x16x32_bf16 v[34:37], v[190:193], v[206:209], v[34:37]
	v_mfma_f32_16x16x32_bf16 v[22:25], v[174:177], v[210:213], v[22:25]
	v_mfma_f32_16x16x32_bf16 v[22:25], v[182:185], v[214:217], v[22:25]
	v_mfma_f32_16x16x32_bf16 v[18:21], v[186:189], v[210:213], v[18:21]
	v_mfma_f32_16x16x32_bf16 v[18:21], v[190:193], v[214:217], v[18:21]
	v_mfma_f32_16x16x32_bf16 v[6:9], v[174:177], v[218:221], v[6:9]
	v_mfma_f32_16x16x32_bf16 v[6:9], v[182:185], v[222:225], v[6:9]
	v_mfma_f32_16x16x32_bf16 v[2:5], v[186:189], v[218:221], v[2:5]
	v_mfma_f32_16x16x32_bf16 v[2:5], v[190:193], v[222:225], v[2:5]
	s_barrier
	s_add_i32 s35, s35, 2
	s_add_u32 s12, s12, 0x100
	s_addc_u32 s13, s13, 0
	s_add_u32 s0, s0, 0x100
	s_addc_u32 s1, s1, 0
	s_cmp_gt_u32 s35, 61
	s_cbranch_scc0 .LBB0_572
	s_and_b64 vcc, exec, s[10:11]
	s_cbranch_vccz .LBB0_575
	s_barrier

.LBB0_881:
	s_and_b32 s98, s30, 3
	s_and_b32 s99, s28, 7
	s_lshl_b32 s98, s98, 6
	s_lshl_b32 s99, s99, 5
	v_and_b32_e32 v244, 63, v0
	v_mul_u32_u24_e32 v245, 43, v244
	v_lshrrev_b32_e32 v245, 10, v245
	v_mul_u32_u24_e32 v245, 24, v245
	v_sub_u32_e32 v244, v244, v245
	v_lshrrev_b32_e32 v245, 6, v0
	v_mad_u32_u24 v244, v245, 24, v244
	v_cmp_gt_u32_e32 vcc, 0x80, v244
	v_and_b32_e32 v245, 63, v244
	v_add_u32_e32 v245, s98, v245
	v_lshrrev_b32_e32 v246, 6, v244
	v_subrev_u32_e32 v247, 0x80, v244
	v_and_b32_e32 v248, 31, v247
	v_add_u32_e32 v248, s99, v248
	v_lshrrev_b32_e32 v247, 5, v247
	v_cndmask_b32_e32 v245, v248, v245, vcc
	v_cndmask_b32_e32 v246, v247, v246, vcc
	v_lshlrev_b32_e32 v245, 13, v245
	v_lshl_add_u32 v245, v246, 7, v245
	v_add_u32_e32 v244, 0x80, v245
	v_mov_b32_e32 v245, 0
	v_mov_b32_e32 v246, s10
	v_mov_b32_e32 v247, s11
	v_mov_b32_e32 v248, s38
	v_mov_b32_e32 v249, s39
	v_cndmask_b32_e32 v246, v248, v246, vcc
	v_cndmask_b32_e32 v247, v249, v247, vcc
	v_lshl_add_u64 v[242:243], v[246:247], 0, v[244:245]
	v_add_u32_e32 v252, 0x10000, v155
	s_add_u32 s10, s10, 0x100080
	s_addc_u32 s11, s11, 0
	s_add_u32 s0, s38, 0x100
	v_mov_b32_e32 v4, 0
	s_addc_u32 s1, s39, 0
	s_mov_b32 s12, -2
	v_mov_b32_e32 v5, v4
	v_mov_b32_e32 v6, v4
	v_mov_b32_e32 v7, v4
	v_mov_b32_e32 v8, v4
	v_mov_b32_e32 v9, v4
	v_mov_b32_e32 v10, v4
	v_mov_b32_e32 v11, v4
	v_mov_b32_e32 v20, v4
	v_mov_b32_e32 v21, v4
	v_mov_b32_e32 v22, v4
	v_mov_b32_e32 v23, v4
	v_mov_b32_e32 v24, v4
	v_mov_b32_e32 v25, v4
	v_mov_b32_e32 v26, v4
	v_mov_b32_e32 v27, v4
	v_mov_b32_e32 v36, v4
	v_mov_b32_e32 v37, v4
	v_mov_b32_e32 v38, v4
	v_mov_b32_e32 v39, v4
	v_mov_b32_e32 v40, v4
	v_mov_b32_e32 v41, v4
	v_mov_b32_e32 v42, v4
	v_mov_b32_e32 v43, v4
	v_mov_b32_e32 v52, v4
	v_mov_b32_e32 v53, v4
	v_mov_b32_e32 v54, v4
	v_mov_b32_e32 v55, v4
	v_mov_b32_e32 v56, v4
	v_mov_b32_e32 v57, v4
	v_mov_b32_e32 v58, v4
	v_mov_b32_e32 v59, v4
	v_mov_b32_e32 v12, v4
	v_mov_b32_e32 v13, v4
	v_mov_b32_e32 v14, v4
	v_mov_b32_e32 v15, v4
	v_mov_b32_e32 v16, v4
	v_mov_b32_e32 v17, v4
	v_mov_b32_e32 v18, v4
	v_mov_b32_e32 v19, v4
	v_mov_b32_e32 v28, v4
	v_mov_b32_e32 v29, v4
	v_mov_b32_e32 v30, v4
	v_mov_b32_e32 v31, v4
	v_mov_b32_e32 v32, v4
	v_mov_b32_e32 v33, v4
	v_mov_b32_e32 v34, v4
	v_mov_b32_e32 v35, v4
	v_mov_b32_e32 v44, v4
	v_mov_b32_e32 v45, v4
	v_mov_b32_e32 v46, v4
	v_mov_b32_e32 v47, v4
	v_mov_b32_e32 v48, v4
	v_mov_b32_e32 v49, v4
	v_mov_b32_e32 v50, v4
	v_mov_b32_e32 v51, v4
	v_mov_b32_e32 v60, v4
	v_mov_b32_e32 v61, v4
	v_mov_b32_e32 v62, v4
	v_mov_b32_e32 v63, v4
	v_mov_b32_e32 v64, v4
	v_mov_b32_e32 v65, v4
	v_mov_b32_e32 v66, v4
	v_mov_b32_e32 v67, v4
	v_mov_b32_e32 v68, v4
	v_mov_b32_e32 v69, v4
	v_mov_b32_e32 v70, v4
	v_mov_b32_e32 v71, v4
	v_mov_b32_e32 v72, v4
	v_mov_b32_e32 v73, v4
	v_mov_b32_e32 v74, v4
	v_mov_b32_e32 v75, v4
	v_mov_b32_e32 v84, v4
	v_mov_b32_e32 v85, v4
	v_mov_b32_e32 v86, v4
	v_mov_b32_e32 v87, v4
	v_mov_b32_e32 v88, v4
	v_mov_b32_e32 v89, v4
	v_mov_b32_e32 v90, v4
	v_mov_b32_e32 v91, v4
	v_mov_b32_e32 v100, v4
	v_mov_b32_e32 v101, v4
	v_mov_b32_e32 v102, v4
	v_mov_b32_e32 v103, v4
	v_mov_b32_e32 v104, v4
	v_mov_b32_e32 v105, v4
	v_mov_b32_e32 v106, v4
	v_mov_b32_e32 v107, v4
	v_mov_b32_e32 v116, v4
	v_mov_b32_e32 v117, v4
	v_mov_b32_e32 v118, v4
	v_mov_b32_e32 v119, v4
	v_mov_b32_e32 v120, v4
	v_mov_b32_e32 v121, v4
	v_mov_b32_e32 v122, v4
	v_mov_b32_e32 v123, v4
	v_mov_b32_e32 v76, v4
	v_mov_b32_e32 v77, v4
	v_mov_b32_e32 v78, v4
	v_mov_b32_e32 v79, v4
	v_mov_b32_e32 v80, v4
	v_mov_b32_e32 v81, v4
	v_mov_b32_e32 v82, v4
	v_mov_b32_e32 v83, v4
	v_mov_b32_e32 v92, v4
	v_mov_b32_e32 v93, v4
	v_mov_b32_e32 v94, v4
	v_mov_b32_e32 v95, v4
	v_mov_b32_e32 v96, v4
	v_mov_b32_e32 v97, v4
	v_mov_b32_e32 v98, v4
	v_mov_b32_e32 v99, v4
	v_mov_b32_e32 v108, v4
	v_mov_b32_e32 v109, v4
	v_mov_b32_e32 v110, v4
	v_mov_b32_e32 v111, v4
	v_mov_b32_e32 v112, v4
	v_mov_b32_e32 v113, v4
	v_mov_b32_e32 v114, v4
	v_mov_b32_e32 v115, v4
	v_mov_b32_e32 v124, v4
	v_mov_b32_e32 v125, v4
	v_mov_b32_e32 v126, v4
	v_mov_b32_e32 v127, v4
	v_mov_b32_e32 v128, v4
	v_mov_b32_e32 v129, v4
	v_mov_b32_e32 v130, v4
	v_mov_b32_e32 v131, v4
.LBB0_882:
	s_add_u32 s20, s10, 0xfff00080
	s_addc_u32 s21, s11, -1
	s_cmp_eq_u32 s12, 60
	s_cselect_b32 s43, s55, s21
	s_cselect_b32 s42, s54, s20
	s_cselect_b32 s39, s37, s1
	s_cselect_b32 s38, s36, s0
	s_cmp_lt_i32 s12, 57
	s_cselect_b32 s100, 0x100, 0
	s_mov_b32 s101, 0
	v_lshl_add_u64 v[242:243], v[242:243], 0, s[100:101]
	s_add_i32 m0, s29, 0xc000
	ds_read_b128 v[146:149], v252
	ds_read_b128 v[150:153], v252 offset:1024
	global_load_lds_dwordx4 v140, s[10:11]
	s_add_i32 m0, s29, 0xe000
	ds_read_b128 v[158:161], v252 offset:2048
	ds_read_b128 v[162:165], v252 offset:3072
	global_load_lds_dwordx4 v142, s[10:11]
	ds_read_b128 v[166:169], v252 offset:16384
	ds_read_b128 v[170:173], v252 offset:17408
	ds_read_b128 v[174:177], v252 offset:18432
	ds_read_b128 v[186:189], v252 offset:19456
	ds_read_b128 v[190:193], v157
	ds_read_b128 v[194:197], v157 offset:1024
	ds_read_b128 v[198:201], v157 offset:2048
	ds_read_b128 v[202:205], v157 offset:3072
	ds_read_b128 v[206:209], v157 offset:4096
	ds_read_b128 v[210:213], v157 offset:5120
	ds_read_b128 v[214:217], v157 offset:6144
	ds_read_b128 v[218:221], v157 offset:7168
	s_waitcnt vmcnt(8)
	s_mov_b32 m0, 0x21800
	s_mov_b64 exec, 0xffffff
	s_waitcnt lgkmcnt(0)
	global_load_lds_dword v[242:243], off
	s_mov_b64 exec, -1
	s_barrier
	v_mfma_f32_16x16x32_bf16 v[128:131], v[146:149], v[190:193], v[128:131]
	v_mfma_f32_16x16x32_bf16 v[128:131], v[150:153], v[194:197], v[128:131]
	v_mfma_f32_16x16x32_bf16 v[124:127], v[158:161], v[190:193], v[124:127]
	v_mfma_f32_16x16x32_bf16 v[124:127], v[162:165], v[194:197], v[124:127]
	v_mfma_f32_16x16x32_bf16 v[112:115], v[146:149], v[198:201], v[112:115]
	v_mfma_f32_16x16x32_bf16 v[112:115], v[150:153], v[202:205], v[112:115]
	v_mfma_f32_16x16x32_bf16 v[108:111], v[158:161], v[198:201], v[108:111]
	v_mfma_f32_16x16x32_bf16 v[108:111], v[162:165], v[202:205], v[108:111]
	v_mfma_f32_16x16x32_bf16 v[96:99], v[146:149], v[206:209], v[96:99]
	v_mfma_f32_16x16x32_bf16 v[96:99], v[150:153], v[210:213], v[96:99]
	v_mfma_f32_16x16x32_bf16 v[92:95], v[158:161], v[206:209], v[92:95]
	v_mfma_f32_16x16x32_bf16 v[92:95], v[162:165], v[210:213], v[92:95]
	v_mfma_f32_16x16x32_bf16 v[80:83], v[146:149], v[214:217], v[80:83]
	v_mfma_f32_16x16x32_bf16 v[80:83], v[150:153], v[218:221], v[80:83]
	v_mfma_f32_16x16x32_bf16 v[76:79], v[158:161], v[214:217], v[76:79]
	v_mfma_f32_16x16x32_bf16 v[76:79], v[162:165], v[218:221], v[76:79]
	v_mfma_f32_16x16x32_bf16 v[120:123], v[166:169], v[190:193], v[120:123]
	v_mfma_f32_16x16x32_bf16 v[120:123], v[170:173], v[194:197], v[120:123]
	v_mfma_f32_16x16x32_bf16 v[116:119], v[174:177], v[190:193], v[116:119]
	v_mfma_f32_16x16x32_bf16 v[116:119], v[186:189], v[194:197], v[116:119]
	v_mfma_f32_16x16x32_bf16 v[104:107], v[166:169], v[198:201], v[104:107]
	v_mfma_f32_16x16x32_bf16 v[104:107], v[170:173], v[202:205], v[104:107]
	v_mfma_f32_16x16x32_bf16 v[100:103], v[174:177], v[198:201], v[100:103]
	v_mfma_f32_16x16x32_bf16 v[100:103], v[186:189], v[202:205], v[100:103]
	v_mfma_f32_16x16x32_bf16 v[88:91], v[166:169], v[206:209], v[88:91]
	v_mfma_f32_16x16x32_bf16 v[88:91], v[170:173], v[210:213], v[88:91]
	v_mfma_f32_16x16x32_bf16 v[84:87], v[174:177], v[206:209], v[84:87]
	v_mfma_f32_16x16x32_bf16 v[84:87], v[186:189], v[210:213], v[84:87]
	v_mfma_f32_16x16x32_bf16 v[72:75], v[166:169], v[214:217], v[72:75]
	v_mfma_f32_16x16x32_bf16 v[72:75], v[170:173], v[218:221], v[72:75]
	v_mfma_f32_16x16x32_bf16 v[68:71], v[174:177], v[214:217], v[68:71]
	v_mfma_f32_16x16x32_bf16 v[68:71], v[186:189], v[218:221], v[68:71]
	s_barrier
	s_add_i32 m0, s58, 0x10000
	ds_read_b128 v[190:193], v157 offset:16384
	ds_read_b128 v[194:197], v157 offset:17408
	global_load_lds_dwordx4 v134, s[38:39]
	s_add_i32 m0, s58, 0x12000
	s_add_u32 s98, s38, 0x100000
	s_addc_u32 s99, s39, 0
	ds_read_b128 v[198:201], v157 offset:18432
	global_load_lds_dwordx4 v138, s[38:39]
	s_add_i32 m0, s58, 0x14000
	ds_read_b128 v[202:205], v157 offset:19456
	ds_read_b128 v[206:209], v157 offset:20480
	global_load_lds_dwordx4 v134, s[98:99]
	s_add_i32 m0, s58, 0x16000
	ds_read_b128 v[210:213], v157 offset:21504
	ds_read_b128 v[214:217], v157 offset:22528
	global_load_lds_dwordx4 v138, s[98:99]
	s_mov_b32 m0, s29
	ds_read_b128 v[218:221], v157 offset:23552
	global_load_lds_dwordx4 v132, s[42:43]
	s_mov_b32 m0, s31
	s_nop 0
	global_load_lds_dwordx4 v136, s[42:43]
	s_waitcnt vmcnt(9)
	s_waitcnt lgkmcnt(0)
	s_barrier
	v_mfma_f32_16x16x32_bf16 v[64:67], v[146:149], v[190:193], v[64:67]
	v_mfma_f32_16x16x32_bf16 v[64:67], v[150:153], v[194:197], v[64:67]
	v_mfma_f32_16x16x32_bf16 v[60:63], v[158:161], v[190:193], v[60:63]
	v_mfma_f32_16x16x32_bf16 v[60:63], v[162:165], v[194:197], v[60:63]
	v_mfma_f32_16x16x32_bf16 v[48:51], v[146:149], v[198:201], v[48:51]
	v_mfma_f32_16x16x32_bf16 v[48:51], v[150:153], v[202:205], v[48:51]
	v_mfma_f32_16x16x32_bf16 v[44:47], v[158:161], v[198:201], v[44:47]
	v_mfma_f32_16x16x32_bf16 v[44:47], v[162:165], v[202:205], v[44:47]
	v_mfma_f32_16x16x32_bf16 v[32:35], v[146:149], v[206:209], v[32:35]
	v_mfma_f32_16x16x32_bf16 v[32:35], v[150:153], v[210:213], v[32:35]
	v_mfma_f32_16x16x32_bf16 v[28:31], v[158:161], v[206:209], v[28:31]
	v_mfma_f32_16x16x32_bf16 v[28:31], v[162:165], v[210:213], v[28:31]
	v_mfma_f32_16x16x32_bf16 v[16:19], v[146:149], v[214:217], v[16:19]
	v_mfma_f32_16x16x32_bf16 v[16:19], v[150:153], v[218:221], v[16:19]
	v_mfma_f32_16x16x32_bf16 v[12:15], v[158:161], v[214:217], v[12:15]
	v_mfma_f32_16x16x32_bf16 v[12:15], v[162:165], v[218:221], v[12:15]
	v_mfma_f32_16x16x32_bf16 v[56:59], v[166:169], v[190:193], v[56:59]
	v_mfma_f32_16x16x32_bf16 v[56:59], v[170:173], v[194:197], v[56:59]
	v_mfma_f32_16x16x32_bf16 v[52:55], v[174:177], v[190:193], v[52:55]
	v_mfma_f32_16x16x32_bf16 v[52:55], v[186:189], v[194:197], v[52:55]
	v_mfma_f32_16x16x32_bf16 v[40:43], v[166:169], v[198:201], v[40:43]
	v_mfma_f32_16x16x32_bf16 v[40:43], v[170:173], v[202:205], v[40:43]
	v_mfma_f32_16x16x32_bf16 v[36:39], v[174:177], v[198:201], v[36:39]
	v_mfma_f32_16x16x32_bf16 v[36:39], v[186:189], v[202:205], v[36:39]
	v_mfma_f32_16x16x32_bf16 v[24:27], v[166:169], v[206:209], v[24:27]
	v_mfma_f32_16x16x32_bf16 v[24:27], v[170:173], v[210:213], v[24:27]
	v_mfma_f32_16x16x32_bf16 v[20:23], v[174:177], v[206:209], v[20:23]
	v_mfma_f32_16x16x32_bf16 v[20:23], v[186:189], v[210:213], v[20:23]
	v_mfma_f32_16x16x32_bf16 v[8:11], v[166:169], v[214:217], v[8:11]
	v_mfma_f32_16x16x32_bf16 v[8:11], v[170:173], v[218:221], v[8:11]
	v_mfma_f32_16x16x32_bf16 v[4:7], v[174:177], v[214:217], v[4:7]
	v_mfma_f32_16x16x32_bf16 v[4:7], v[186:189], v[218:221], v[4:7]
	s_barrier
	s_add_u32 s100, s42, 0x100000
	s_addc_u32 s101, s43, 0
	s_mov_b32 m0, s59
	ds_read_b128 v[146:149], v252 offset:32768
	ds_read_b128 v[150:153], v252 offset:33792
	global_load_lds_dwordx4 v132, s[100:101]
	s_mov_b32 m0, s94
	ds_read_b128 v[158:161], v252 offset:34816
	ds_read_b128 v[162:165], v252 offset:35840
	global_load_lds_dwordx4 v136, s[100:101]
	ds_read_b128 v[166:169], v252 offset:49152
	ds_read_b128 v[170:173], v252 offset:50176
	ds_read_b128 v[174:177], v252 offset:51200
	ds_read_b128 v[186:189], v252 offset:52224
	ds_read_b128 v[190:193], v157 offset:32768
	ds_read_b128 v[194:197], v157 offset:33792
	ds_read_b128 v[198:201], v157 offset:34816
	ds_read_b128 v[202:205], v157 offset:35840
	ds_read_b128 v[206:209], v157 offset:36864
	ds_read_b128 v[210:213], v157 offset:37888
	ds_read_b128 v[214:217], v157 offset:38912
	ds_read_b128 v[218:221], v157 offset:39936
	s_waitcnt vmcnt(9)
	s_waitcnt lgkmcnt(0)
	s_barrier
	v_mfma_f32_16x16x32_bf16 v[128:131], v[146:149], v[190:193], v[128:131]
	v_mfma_f32_16x16x32_bf16 v[128:131], v[150:153], v[194:197], v[128:131]
	v_mfma_f32_16x16x32_bf16 v[124:127], v[158:161], v[190:193], v[124:127]
	v_mfma_f32_16x16x32_bf16 v[124:127], v[162:165], v[194:197], v[124:127]
	v_mfma_f32_16x16x32_bf16 v[112:115], v[146:149], v[198:201], v[112:115]
	v_mfma_f32_16x16x32_bf16 v[112:115], v[150:153], v[202:205], v[112:115]
	v_mfma_f32_16x16x32_bf16 v[108:111], v[158:161], v[198:201], v[108:111]
	v_mfma_f32_16x16x32_bf16 v[108:111], v[162:165], v[202:205], v[108:111]
	v_mfma_f32_16x16x32_bf16 v[96:99], v[146:149], v[206:209], v[96:99]
	v_mfma_f32_16x16x32_bf16 v[96:99], v[150:153], v[210:213], v[96:99]
	v_mfma_f32_16x16x32_bf16 v[92:95], v[158:161], v[206:209], v[92:95]
	v_mfma_f32_16x16x32_bf16 v[92:95], v[162:165], v[210:213], v[92:95]
	v_mfma_f32_16x16x32_bf16 v[80:83], v[146:149], v[214:217], v[80:83]
	v_mfma_f32_16x16x32_bf16 v[80:83], v[150:153], v[218:221], v[80:83]
	v_mfma_f32_16x16x32_bf16 v[76:79], v[158:161], v[214:217], v[76:79]
	v_mfma_f32_16x16x32_bf16 v[76:79], v[162:165], v[218:221], v[76:79]
	v_mfma_f32_16x16x32_bf16 v[120:123], v[166:169], v[190:193], v[120:123]
	v_mfma_f32_16x16x32_bf16 v[120:123], v[170:173], v[194:197], v[120:123]
	v_mfma_f32_16x16x32_bf16 v[116:119], v[174:177], v[190:193], v[116:119]
	v_mfma_f32_16x16x32_bf16 v[116:119], v[186:189], v[194:197], v[116:119]
	v_mfma_f32_16x16x32_bf16 v[104:107], v[166:169], v[198:201], v[104:107]
	v_mfma_f32_16x16x32_bf16 v[104:107], v[170:173], v[202:205], v[104:107]
	v_mfma_f32_16x16x32_bf16 v[100:103], v[174:177], v[198:201], v[100:103]
	v_mfma_f32_16x16x32_bf16 v[100:103], v[186:189], v[202:205], v[100:103]
	v_mfma_f32_16x16x32_bf16 v[88:91], v[166:169], v[206:209], v[88:91]
	v_mfma_f32_16x16x32_bf16 v[88:91], v[170:173], v[210:213], v[88:91]
	v_mfma_f32_16x16x32_bf16 v[84:87], v[174:177], v[206:209], v[84:87]
	v_mfma_f32_16x16x32_bf16 v[84:87], v[186:189], v[210:213], v[84:87]
	v_mfma_f32_16x16x32_bf16 v[72:75], v[166:169], v[214:217], v[72:75]
	v_mfma_f32_16x16x32_bf16 v[72:75], v[170:173], v[218:221], v[72:75]
	v_mfma_f32_16x16x32_bf16 v[68:71], v[174:177], v[214:217], v[68:71]
	v_mfma_f32_16x16x32_bf16 v[68:71], v[186:189], v[218:221], v[68:71]
	s_barrier
	s_add_u32 s38, s38, 0x80
	s_addc_u32 s39, s39, 0
	s_add_i32 m0, s58, 0x18000
	ds_read_b128 v[190:193], v157 offset:49152
	ds_read_b128 v[194:197], v157 offset:50176
	global_load_lds_dwordx4 v134, s[38:39]
	s_add_i32 m0, s58, 0x1a000
	s_add_u32 s98, s98, 0x80
	s_addc_u32 s99, s99, 0
	ds_read_b128 v[198:201], v157 offset:51200
	global_load_lds_dwordx4 v138, s[38:39]
	s_add_i32 m0, s58, 0x1c000
	ds_read_b128 v[202:205], v157 offset:52224
	ds_read_b128 v[206:209], v157 offset:53248
	global_load_lds_dwordx4 v134, s[98:99]
	s_add_i32 m0, s58, 0x1e000
	s_add_u32 s42, s42, 0x80
	s_addc_u32 s43, s43, 0
	ds_read_b128 v[210:213], v157 offset:54272
	ds_read_b128 v[214:217], v157 offset:55296
	global_load_lds_dwordx4 v138, s[98:99]
	s_mov_b32 m0, s14
	ds_read_b128 v[218:221], v157 offset:56320
	global_load_lds_dwordx4 v132, s[42:43]
	s_mov_b32 m0, s15
	s_nop 0
	global_load_lds_dwordx4 v136, s[42:43]
	s_waitcnt vmcnt(8)
	s_waitcnt lgkmcnt(0)
	s_barrier
	v_mfma_f32_16x16x32_bf16 v[64:67], v[146:149], v[190:193], v[64:67]
	v_mfma_f32_16x16x32_bf16 v[64:67], v[150:153], v[194:197], v[64:67]
	v_mfma_f32_16x16x32_bf16 v[60:63], v[158:161], v[190:193], v[60:63]
	v_mfma_f32_16x16x32_bf16 v[60:63], v[162:165], v[194:197], v[60:63]
	v_mfma_f32_16x16x32_bf16 v[48:51], v[146:149], v[198:201], v[48:51]
	v_mfma_f32_16x16x32_bf16 v[48:51], v[150:153], v[202:205], v[48:51]
	v_mfma_f32_16x16x32_bf16 v[44:47], v[158:161], v[198:201], v[44:47]
	v_mfma_f32_16x16x32_bf16 v[44:47], v[162:165], v[202:205], v[44:47]
	v_mfma_f32_16x16x32_bf16 v[32:35], v[146:149], v[206:209], v[32:35]
	v_mfma_f32_16x16x32_bf16 v[32:35], v[150:153], v[210:213], v[32:35]
	v_mfma_f32_16x16x32_bf16 v[28:31], v[158:161], v[206:209], v[28:31]
	v_mfma_f32_16x16x32_bf16 v[28:31], v[162:165], v[210:213], v[28:31]
	v_mfma_f32_16x16x32_bf16 v[16:19], v[146:149], v[214:217], v[16:19]
	v_mfma_f32_16x16x32_bf16 v[16:19], v[150:153], v[218:221], v[16:19]
	v_mfma_f32_16x16x32_bf16 v[12:15], v[158:161], v[214:217], v[12:15]
	v_mfma_f32_16x16x32_bf16 v[12:15], v[162:165], v[218:221], v[12:15]
	v_mfma_f32_16x16x32_bf16 v[56:59], v[166:169], v[190:193], v[56:59]
	v_mfma_f32_16x16x32_bf16 v[56:59], v[170:173], v[194:197], v[56:59]
	v_mfma_f32_16x16x32_bf16 v[52:55], v[174:177], v[190:193], v[52:55]
	v_mfma_f32_16x16x32_bf16 v[52:55], v[186:189], v[194:197], v[52:55]
	v_mfma_f32_16x16x32_bf16 v[40:43], v[166:169], v[198:201], v[40:43]
	v_mfma_f32_16x16x32_bf16 v[40:43], v[170:173], v[202:205], v[40:43]
	v_mfma_f32_16x16x32_bf16 v[36:39], v[174:177], v[198:201], v[36:39]
	v_mfma_f32_16x16x32_bf16 v[36:39], v[186:189], v[202:205], v[36:39]
	v_mfma_f32_16x16x32_bf16 v[24:27], v[166:169], v[206:209], v[24:27]
	v_mfma_f32_16x16x32_bf16 v[24:27], v[170:173], v[210:213], v[24:27]
	v_mfma_f32_16x16x32_bf16 v[20:23], v[174:177], v[206:209], v[20:23]
	v_mfma_f32_16x16x32_bf16 v[20:23], v[186:189], v[210:213], v[20:23]
	v_mfma_f32_16x16x32_bf16 v[8:11], v[166:169], v[214:217], v[8:11]
	v_mfma_f32_16x16x32_bf16 v[8:11], v[170:173], v[218:221], v[8:11]
	v_mfma_f32_16x16x32_bf16 v[4:7], v[174:177], v[214:217], v[4:7]
	v_mfma_f32_16x16x32_bf16 v[4:7], v[186:189], v[218:221], v[4:7]
	s_barrier
	s_add_i32 s12, s12, 2
	s_add_u32 s10, s10, 0x100
	s_addc_u32 s11, s11, 0
	s_add_u32 s0, s0, 0x100
	s_addc_u32 s1, s1, 0
	s_cmp_gt_u32 s12, 61
	s_cbranch_scc0 .LBB0_882
	s_and_b64 vcc, exec, s[48:49]
	s_cbranch_vccz .LBB0_885
	s_barrier

.LBB0_1225:
	s_and_b32 s98, s59, 3
	s_and_b32 s99, s58, 7
	s_lshl_b32 s98, s98, 6
	s_lshl_b32 s99, s99, 5
	v_and_b32_e32 v244, 63, v0
	v_mul_u32_u24_e32 v245, 43, v244
	v_lshrrev_b32_e32 v245, 10, v245
	v_mul_u32_u24_e32 v245, 24, v245
	v_sub_u32_e32 v244, v244, v245
	v_lshrrev_b32_e32 v245, 6, v0
	v_mad_u32_u24 v244, v245, 24, v244
	v_cmp_gt_u32_e32 vcc, 0x80, v244
	v_and_b32_e32 v245, 63, v244
	v_add_u32_e32 v245, s98, v245
	v_lshrrev_b32_e32 v246, 6, v244
	v_subrev_u32_e32 v247, 0x80, v244
	v_and_b32_e32 v248, 31, v247
	v_add_u32_e32 v248, s99, v248
	v_lshrrev_b32_e32 v247, 5, v247
	v_cndmask_b32_e32 v245, v248, v245, vcc
	v_cndmask_b32_e32 v246, v247, v246, vcc
	v_lshlrev_b32_e32 v245, 13, v245
	v_lshl_add_u32 v245, v246, 7, v245
	v_add_u32_e32 v244, 0x80, v245
	v_mov_b32_e32 v245, 0
	v_mov_b32_e32 v246, s10
	v_mov_b32_e32 v247, s11
	v_mov_b32_e32 v248, s28
	v_mov_b32_e32 v249, s29
	v_cndmask_b32_e32 v246, v248, v246, vcc
	v_cndmask_b32_e32 v247, v249, v247, vcc
	v_lshl_add_u64 v[242:243], v[246:247], 0, v[244:245]
	v_add_u32_e32 v252, 0x10000, v151
	s_add_u32 s10, s10, 0x100080
	s_addc_u32 s11, s11, 0
	s_add_u32 s0, s28, 0x100
	v_mov_b32_e32 v4, 0
	s_addc_u32 s1, s29, 0
	s_mov_b32 s20, -2
	v_mov_b32_e32 v5, v4
	v_mov_b32_e32 v6, v4
	v_mov_b32_e32 v7, v4
	v_mov_b32_e32 v8, v4
	v_mov_b32_e32 v9, v4
	v_mov_b32_e32 v10, v4
	v_mov_b32_e32 v11, v4
	v_mov_b32_e32 v20, v4
	v_mov_b32_e32 v21, v4
	v_mov_b32_e32 v22, v4
	v_mov_b32_e32 v23, v4
	v_mov_b32_e32 v24, v4
	v_mov_b32_e32 v25, v4
	v_mov_b32_e32 v26, v4
	v_mov_b32_e32 v27, v4
	v_mov_b32_e32 v36, v4
	v_mov_b32_e32 v37, v4
	v_mov_b32_e32 v38, v4
	v_mov_b32_e32 v39, v4
	v_mov_b32_e32 v40, v4
	v_mov_b32_e32 v41, v4
	v_mov_b32_e32 v42, v4
	v_mov_b32_e32 v43, v4
	v_mov_b32_e32 v52, v4
	v_mov_b32_e32 v53, v4
	v_mov_b32_e32 v54, v4
	v_mov_b32_e32 v55, v4
	v_mov_b32_e32 v56, v4
	v_mov_b32_e32 v57, v4
	v_mov_b32_e32 v58, v4
	v_mov_b32_e32 v59, v4
	v_mov_b32_e32 v12, v4
	v_mov_b32_e32 v13, v4
	v_mov_b32_e32 v14, v4
	v_mov_b32_e32 v15, v4
	v_mov_b32_e32 v16, v4
	v_mov_b32_e32 v17, v4
	v_mov_b32_e32 v18, v4
	v_mov_b32_e32 v19, v4
	v_mov_b32_e32 v28, v4
	v_mov_b32_e32 v29, v4
	v_mov_b32_e32 v30, v4
	v_mov_b32_e32 v31, v4
	v_mov_b32_e32 v32, v4
	v_mov_b32_e32 v33, v4
	v_mov_b32_e32 v34, v4
	v_mov_b32_e32 v35, v4
	v_mov_b32_e32 v44, v4
	v_mov_b32_e32 v45, v4
	v_mov_b32_e32 v46, v4
	v_mov_b32_e32 v47, v4
	v_mov_b32_e32 v48, v4
	v_mov_b32_e32 v49, v4
	v_mov_b32_e32 v50, v4
	v_mov_b32_e32 v51, v4
	v_mov_b32_e32 v60, v4
	v_mov_b32_e32 v61, v4
	v_mov_b32_e32 v62, v4
	v_mov_b32_e32 v63, v4
	v_mov_b32_e32 v64, v4
	v_mov_b32_e32 v65, v4
	v_mov_b32_e32 v66, v4
	v_mov_b32_e32 v67, v4
	v_mov_b32_e32 v68, v4
	v_mov_b32_e32 v69, v4
	v_mov_b32_e32 v70, v4
	v_mov_b32_e32 v71, v4
	v_mov_b32_e32 v72, v4
	v_mov_b32_e32 v73, v4
	v_mov_b32_e32 v74, v4
	v_mov_b32_e32 v75, v4
	v_mov_b32_e32 v84, v4
	v_mov_b32_e32 v85, v4
	v_mov_b32_e32 v86, v4
	v_mov_b32_e32 v87, v4
	v_mov_b32_e32 v88, v4
	v_mov_b32_e32 v89, v4
	v_mov_b32_e32 v90, v4
	v_mov_b32_e32 v91, v4
	v_mov_b32_e32 v100, v4
	v_mov_b32_e32 v101, v4
	v_mov_b32_e32 v102, v4
	v_mov_b32_e32 v103, v4
	v_mov_b32_e32 v104, v4
	v_mov_b32_e32 v105, v4
	v_mov_b32_e32 v106, v4
	v_mov_b32_e32 v107, v4
	v_mov_b32_e32 v116, v4
	v_mov_b32_e32 v117, v4
	v_mov_b32_e32 v118, v4
	v_mov_b32_e32 v119, v4
	v_mov_b32_e32 v120, v4
	v_mov_b32_e32 v121, v4
	v_mov_b32_e32 v122, v4
	v_mov_b32_e32 v123, v4
	v_mov_b32_e32 v76, v4
	v_mov_b32_e32 v77, v4
	v_mov_b32_e32 v78, v4
	v_mov_b32_e32 v79, v4
	v_mov_b32_e32 v80, v4
	v_mov_b32_e32 v81, v4
	v_mov_b32_e32 v82, v4
	v_mov_b32_e32 v83, v4
	v_mov_b32_e32 v92, v4
	v_mov_b32_e32 v93, v4
	v_mov_b32_e32 v94, v4
	v_mov_b32_e32 v95, v4
	v_mov_b32_e32 v96, v4
	v_mov_b32_e32 v97, v4
	v_mov_b32_e32 v98, v4
	v_mov_b32_e32 v99, v4
	v_mov_b32_e32 v108, v4
	v_mov_b32_e32 v109, v4
	v_mov_b32_e32 v110, v4
	v_mov_b32_e32 v111, v4
	v_mov_b32_e32 v112, v4
	v_mov_b32_e32 v113, v4
	v_mov_b32_e32 v114, v4
	v_mov_b32_e32 v115, v4
	v_mov_b32_e32 v124, v4
	v_mov_b32_e32 v125, v4
	v_mov_b32_e32 v126, v4
	v_mov_b32_e32 v127, v4
	v_mov_b32_e32 v128, v4
	v_mov_b32_e32 v129, v4
	v_mov_b32_e32 v130, v4
	v_mov_b32_e32 v131, v4
.LBB0_1226:
	s_add_u32 s21, s10, 0xfff00080
	s_addc_u32 s22, s11, -1
	s_cmp_eq_u32 s20, 60
	s_cselect_b32 s31, s53, s22
	s_cselect_b32 s30, s52, s21
	s_cselect_b32 s29, s55, s1
	s_cselect_b32 s28, s54, s0
	s_cmp_lt_i32 s20, 57
	s_cselect_b32 s100, 0x100, 0
	s_mov_b32 s101, 0
	v_lshl_add_u64 v[242:243], v[242:243], 0, s[100:101]
	s_add_i32 m0, s8, 0xc000
	ds_read_b128 v[144:147], v252
	ds_read_b128 v[154:157], v252 offset:1024
	global_load_lds_dwordx4 v140, s[10:11]
	s_add_i32 m0, s8, 0xe000
	ds_read_b128 v[158:161], v252 offset:2048
	ds_read_b128 v[162:165], v252 offset:3072
	global_load_lds_dwordx4 v142, s[10:11]
	ds_read_b128 v[166:169], v252 offset:16384
	ds_read_b128 v[170:173], v252 offset:17408
	ds_read_b128 v[174:177], v252 offset:18432
	ds_read_b128 v[186:189], v252 offset:19456
	ds_read_b128 v[190:193], v153
	ds_read_b128 v[194:197], v153 offset:1024
	ds_read_b128 v[198:201], v153 offset:2048
	ds_read_b128 v[202:205], v153 offset:3072
	ds_read_b128 v[206:209], v153 offset:4096
	ds_read_b128 v[210:213], v153 offset:5120
	ds_read_b128 v[214:217], v153 offset:6144
	ds_read_b128 v[218:221], v153 offset:7168
	s_waitcnt vmcnt(8)
	s_mov_b32 m0, 0x21800
	s_mov_b64 exec, 0xffffff
	s_waitcnt lgkmcnt(0)
	global_load_lds_dword v[242:243], off
	s_mov_b64 exec, -1
	s_barrier
	v_mfma_f32_16x16x32_bf16 v[128:131], v[144:147], v[190:193], v[128:131]
	v_mfma_f32_16x16x32_bf16 v[128:131], v[154:157], v[194:197], v[128:131]
	v_mfma_f32_16x16x32_bf16 v[124:127], v[158:161], v[190:193], v[124:127]
	v_mfma_f32_16x16x32_bf16 v[124:127], v[162:165], v[194:197], v[124:127]
	v_mfma_f32_16x16x32_bf16 v[112:115], v[144:147], v[198:201], v[112:115]
	v_mfma_f32_16x16x32_bf16 v[112:115], v[154:157], v[202:205], v[112:115]
	v_mfma_f32_16x16x32_bf16 v[108:111], v[158:161], v[198:201], v[108:111]
	v_mfma_f32_16x16x32_bf16 v[108:111], v[162:165], v[202:205], v[108:111]
	v_mfma_f32_16x16x32_bf16 v[96:99], v[144:147], v[206:209], v[96:99]
	v_mfma_f32_16x16x32_bf16 v[96:99], v[154:157], v[210:213], v[96:99]
	v_mfma_f32_16x16x32_bf16 v[92:95], v[158:161], v[206:209], v[92:95]
	v_mfma_f32_16x16x32_bf16 v[92:95], v[162:165], v[210:213], v[92:95]
	v_mfma_f32_16x16x32_bf16 v[80:83], v[144:147], v[214:217], v[80:83]
	v_mfma_f32_16x16x32_bf16 v[80:83], v[154:157], v[218:221], v[80:83]
	v_mfma_f32_16x16x32_bf16 v[76:79], v[158:161], v[214:217], v[76:79]
	v_mfma_f32_16x16x32_bf16 v[76:79], v[162:165], v[218:221], v[76:79]
	v_mfma_f32_16x16x32_bf16 v[120:123], v[166:169], v[190:193], v[120:123]
	v_mfma_f32_16x16x32_bf16 v[120:123], v[170:173], v[194:197], v[120:123]
	v_mfma_f32_16x16x32_bf16 v[116:119], v[174:177], v[190:193], v[116:119]
	v_mfma_f32_16x16x32_bf16 v[116:119], v[186:189], v[194:197], v[116:119]
	v_mfma_f32_16x16x32_bf16 v[104:107], v[166:169], v[198:201], v[104:107]
	v_mfma_f32_16x16x32_bf16 v[104:107], v[170:173], v[202:205], v[104:107]
	v_mfma_f32_16x16x32_bf16 v[100:103], v[174:177], v[198:201], v[100:103]
	v_mfma_f32_16x16x32_bf16 v[100:103], v[186:189], v[202:205], v[100:103]
	v_mfma_f32_16x16x32_bf16 v[88:91], v[166:169], v[206:209], v[88:91]
	v_mfma_f32_16x16x32_bf16 v[88:91], v[170:173], v[210:213], v[88:91]
	v_mfma_f32_16x16x32_bf16 v[84:87], v[174:177], v[206:209], v[84:87]
	v_mfma_f32_16x16x32_bf16 v[84:87], v[186:189], v[210:213], v[84:87]
	v_mfma_f32_16x16x32_bf16 v[72:75], v[166:169], v[214:217], v[72:75]
	v_mfma_f32_16x16x32_bf16 v[72:75], v[170:173], v[218:221], v[72:75]
	v_mfma_f32_16x16x32_bf16 v[68:71], v[174:177], v[214:217], v[68:71]
	v_mfma_f32_16x16x32_bf16 v[68:71], v[186:189], v[218:221], v[68:71]
	s_barrier
	s_add_i32 m0, s38, 0x10000
	ds_read_b128 v[190:193], v153 offset:16384
	ds_read_b128 v[194:197], v153 offset:17408
	global_load_lds_dwordx4 v136, s[28:29]
	s_add_i32 m0, s38, 0x12000
	s_add_u32 s98, s28, 0x100000
	s_addc_u32 s99, s29, 0
	ds_read_b128 v[198:201], v153 offset:18432
	global_load_lds_dwordx4 v132, s[28:29]
	s_add_i32 m0, s38, 0x14000
	ds_read_b128 v[202:205], v153 offset:19456
	ds_read_b128 v[206:209], v153 offset:20480
	global_load_lds_dwordx4 v136, s[98:99]
	s_add_i32 m0, s38, 0x16000
	ds_read_b128 v[210:213], v153 offset:21504
	ds_read_b128 v[214:217], v153 offset:22528
	global_load_lds_dwordx4 v132, s[98:99]
	s_mov_b32 m0, s8
	ds_read_b128 v[218:221], v153 offset:23552
	global_load_lds_dwordx4 v138, s[30:31]
	s_mov_b32 m0, s9
	s_nop 0
	global_load_lds_dwordx4 v134, s[30:31]
	s_waitcnt vmcnt(9)
	s_waitcnt lgkmcnt(0)
	s_barrier
	v_mfma_f32_16x16x32_bf16 v[64:67], v[144:147], v[190:193], v[64:67]
	v_mfma_f32_16x16x32_bf16 v[64:67], v[154:157], v[194:197], v[64:67]
	v_mfma_f32_16x16x32_bf16 v[60:63], v[158:161], v[190:193], v[60:63]
	v_mfma_f32_16x16x32_bf16 v[60:63], v[162:165], v[194:197], v[60:63]
	v_mfma_f32_16x16x32_bf16 v[48:51], v[144:147], v[198:201], v[48:51]
	v_mfma_f32_16x16x32_bf16 v[48:51], v[154:157], v[202:205], v[48:51]
	v_mfma_f32_16x16x32_bf16 v[44:47], v[158:161], v[198:201], v[44:47]
	v_mfma_f32_16x16x32_bf16 v[44:47], v[162:165], v[202:205], v[44:47]
	v_mfma_f32_16x16x32_bf16 v[32:35], v[144:147], v[206:209], v[32:35]
	v_mfma_f32_16x16x32_bf16 v[32:35], v[154:157], v[210:213], v[32:35]
	v_mfma_f32_16x16x32_bf16 v[28:31], v[158:161], v[206:209], v[28:31]
	v_mfma_f32_16x16x32_bf16 v[28:31], v[162:165], v[210:213], v[28:31]
	v_mfma_f32_16x16x32_bf16 v[16:19], v[144:147], v[214:217], v[16:19]
	v_mfma_f32_16x16x32_bf16 v[16:19], v[154:157], v[218:221], v[16:19]
	v_mfma_f32_16x16x32_bf16 v[12:15], v[158:161], v[214:217], v[12:15]
	v_mfma_f32_16x16x32_bf16 v[12:15], v[162:165], v[218:221], v[12:15]
	v_mfma_f32_16x16x32_bf16 v[56:59], v[166:169], v[190:193], v[56:59]
	v_mfma_f32_16x16x32_bf16 v[56:59], v[170:173], v[194:197], v[56:59]
	v_mfma_f32_16x16x32_bf16 v[52:55], v[174:177], v[190:193], v[52:55]
	v_mfma_f32_16x16x32_bf16 v[52:55], v[186:189], v[194:197], v[52:55]
	v_mfma_f32_16x16x32_bf16 v[40:43], v[166:169], v[198:201], v[40:43]
	v_mfma_f32_16x16x32_bf16 v[40:43], v[170:173], v[202:205], v[40:43]
	v_mfma_f32_16x16x32_bf16 v[36:39], v[174:177], v[198:201], v[36:39]
	v_mfma_f32_16x16x32_bf16 v[36:39], v[186:189], v[202:205], v[36:39]
	v_mfma_f32_16x16x32_bf16 v[24:27], v[166:169], v[206:209], v[24:27]
	v_mfma_f32_16x16x32_bf16 v[24:27], v[170:173], v[210:213], v[24:27]
	v_mfma_f32_16x16x32_bf16 v[20:23], v[174:177], v[206:209], v[20:23]
	v_mfma_f32_16x16x32_bf16 v[20:23], v[186:189], v[210:213], v[20:23]
	v_mfma_f32_16x16x32_bf16 v[8:11], v[166:169], v[214:217], v[8:11]
	v_mfma_f32_16x16x32_bf16 v[8:11], v[170:173], v[218:221], v[8:11]
	v_mfma_f32_16x16x32_bf16 v[4:7], v[174:177], v[214:217], v[4:7]
	v_mfma_f32_16x16x32_bf16 v[4:7], v[186:189], v[218:221], v[4:7]
	s_barrier
	s_add_u32 s100, s30, 0x100000
	s_addc_u32 s101, s31, 0
	s_mov_b32 m0, s16
	ds_read_b128 v[144:147], v252 offset:32768
	ds_read_b128 v[154:157], v252 offset:33792
	global_load_lds_dwordx4 v138, s[100:101]
	s_mov_b32 m0, s17
	ds_read_b128 v[158:161], v252 offset:34816
	ds_read_b128 v[162:165], v252 offset:35840
	global_load_lds_dwordx4 v134, s[100:101]
	ds_read_b128 v[166:169], v252 offset:49152
	ds_read_b128 v[170:173], v252 offset:50176
	ds_read_b128 v[174:177], v252 offset:51200
	ds_read_b128 v[186:189], v252 offset:52224
	ds_read_b128 v[190:193], v153 offset:32768
	ds_read_b128 v[194:197], v153 offset:33792
	ds_read_b128 v[198:201], v153 offset:34816
	ds_read_b128 v[202:205], v153 offset:35840
	ds_read_b128 v[206:209], v153 offset:36864
	ds_read_b128 v[210:213], v153 offset:37888
	ds_read_b128 v[214:217], v153 offset:38912
	ds_read_b128 v[218:221], v153 offset:39936
	s_waitcnt vmcnt(9)
	s_waitcnt lgkmcnt(0)
	s_barrier
	v_mfma_f32_16x16x32_bf16 v[128:131], v[144:147], v[190:193], v[128:131]
	v_mfma_f32_16x16x32_bf16 v[128:131], v[154:157], v[194:197], v[128:131]
	v_mfma_f32_16x16x32_bf16 v[124:127], v[158:161], v[190:193], v[124:127]
	v_mfma_f32_16x16x32_bf16 v[124:127], v[162:165], v[194:197], v[124:127]
	v_mfma_f32_16x16x32_bf16 v[112:115], v[144:147], v[198:201], v[112:115]
	v_mfma_f32_16x16x32_bf16 v[112:115], v[154:157], v[202:205], v[112:115]
	v_mfma_f32_16x16x32_bf16 v[108:111], v[158:161], v[198:201], v[108:111]
	v_mfma_f32_16x16x32_bf16 v[108:111], v[162:165], v[202:205], v[108:111]
	v_mfma_f32_16x16x32_bf16 v[96:99], v[144:147], v[206:209], v[96:99]
	v_mfma_f32_16x16x32_bf16 v[96:99], v[154:157], v[210:213], v[96:99]
	v_mfma_f32_16x16x32_bf16 v[92:95], v[158:161], v[206:209], v[92:95]
	v_mfma_f32_16x16x32_bf16 v[92:95], v[162:165], v[210:213], v[92:95]
	v_mfma_f32_16x16x32_bf16 v[80:83], v[144:147], v[214:217], v[80:83]
	v_mfma_f32_16x16x32_bf16 v[80:83], v[154:157], v[218:221], v[80:83]
	v_mfma_f32_16x16x32_bf16 v[76:79], v[158:161], v[214:217], v[76:79]
	v_mfma_f32_16x16x32_bf16 v[76:79], v[162:165], v[218:221], v[76:79]
	v_mfma_f32_16x16x32_bf16 v[120:123], v[166:169], v[190:193], v[120:123]
	v_mfma_f32_16x16x32_bf16 v[120:123], v[170:173], v[194:197], v[120:123]
	v_mfma_f32_16x16x32_bf16 v[116:119], v[174:177], v[190:193], v[116:119]
	v_mfma_f32_16x16x32_bf16 v[116:119], v[186:189], v[194:197], v[116:119]
	v_mfma_f32_16x16x32_bf16 v[104:107], v[166:169], v[198:201], v[104:107]
	v_mfma_f32_16x16x32_bf16 v[104:107], v[170:173], v[202:205], v[104:107]
	v_mfma_f32_16x16x32_bf16 v[100:103], v[174:177], v[198:201], v[100:103]
	v_mfma_f32_16x16x32_bf16 v[100:103], v[186:189], v[202:205], v[100:103]
	v_mfma_f32_16x16x32_bf16 v[88:91], v[166:169], v[206:209], v[88:91]
	v_mfma_f32_16x16x32_bf16 v[88:91], v[170:173], v[210:213], v[88:91]
	v_mfma_f32_16x16x32_bf16 v[84:87], v[174:177], v[206:209], v[84:87]
	v_mfma_f32_16x16x32_bf16 v[84:87], v[186:189], v[210:213], v[84:87]
	v_mfma_f32_16x16x32_bf16 v[72:75], v[166:169], v[214:217], v[72:75]
	v_mfma_f32_16x16x32_bf16 v[72:75], v[170:173], v[218:221], v[72:75]
	v_mfma_f32_16x16x32_bf16 v[68:71], v[174:177], v[214:217], v[68:71]
	v_mfma_f32_16x16x32_bf16 v[68:71], v[186:189], v[218:221], v[68:71]
	s_barrier
	s_add_u32 s28, s28, 0x80
	s_addc_u32 s29, s29, 0
	s_add_i32 m0, s38, 0x18000
	ds_read_b128 v[190:193], v153 offset:49152
	ds_read_b128 v[194:197], v153 offset:50176
	global_load_lds_dwordx4 v136, s[28:29]
	s_add_i32 m0, s38, 0x1a000
	s_add_u32 s98, s98, 0x80
	s_addc_u32 s99, s99, 0
	ds_read_b128 v[198:201], v153 offset:51200
	global_load_lds_dwordx4 v132, s[28:29]
	s_add_i32 m0, s38, 0x1c000
	ds_read_b128 v[202:205], v153 offset:52224
	ds_read_b128 v[206:209], v153 offset:53248
	global_load_lds_dwordx4 v136, s[98:99]
	s_add_i32 m0, s38, 0x1e000
	s_add_u32 s30, s30, 0x80
	s_addc_u32 s31, s31, 0
	ds_read_b128 v[210:213], v153 offset:54272
	ds_read_b128 v[214:217], v153 offset:55296
	global_load_lds_dwordx4 v132, s[98:99]
	s_mov_b32 m0, s45
	ds_read_b128 v[218:221], v153 offset:56320
	global_load_lds_dwordx4 v138, s[30:31]
	s_mov_b32 m0, s46
	s_nop 0
	global_load_lds_dwordx4 v134, s[30:31]
	s_waitcnt vmcnt(8)
	s_waitcnt lgkmcnt(0)
	s_barrier
	v_mfma_f32_16x16x32_bf16 v[64:67], v[144:147], v[190:193], v[64:67]
	v_mfma_f32_16x16x32_bf16 v[64:67], v[154:157], v[194:197], v[64:67]
	v_mfma_f32_16x16x32_bf16 v[60:63], v[158:161], v[190:193], v[60:63]
	v_mfma_f32_16x16x32_bf16 v[60:63], v[162:165], v[194:197], v[60:63]
	v_mfma_f32_16x16x32_bf16 v[48:51], v[144:147], v[198:201], v[48:51]
	v_mfma_f32_16x16x32_bf16 v[48:51], v[154:157], v[202:205], v[48:51]
	v_mfma_f32_16x16x32_bf16 v[44:47], v[158:161], v[198:201], v[44:47]
	v_mfma_f32_16x16x32_bf16 v[44:47], v[162:165], v[202:205], v[44:47]
	v_mfma_f32_16x16x32_bf16 v[32:35], v[144:147], v[206:209], v[32:35]
	v_mfma_f32_16x16x32_bf16 v[32:35], v[154:157], v[210:213], v[32:35]
	v_mfma_f32_16x16x32_bf16 v[28:31], v[158:161], v[206:209], v[28:31]
	v_mfma_f32_16x16x32_bf16 v[28:31], v[162:165], v[210:213], v[28:31]
	v_mfma_f32_16x16x32_bf16 v[16:19], v[144:147], v[214:217], v[16:19]
	v_mfma_f32_16x16x32_bf16 v[16:19], v[154:157], v[218:221], v[16:19]
	v_mfma_f32_16x16x32_bf16 v[12:15], v[158:161], v[214:217], v[12:15]
	v_mfma_f32_16x16x32_bf16 v[12:15], v[162:165], v[218:221], v[12:15]
	v_mfma_f32_16x16x32_bf16 v[56:59], v[166:169], v[190:193], v[56:59]
	v_mfma_f32_16x16x32_bf16 v[56:59], v[170:173], v[194:197], v[56:59]
	v_mfma_f32_16x16x32_bf16 v[52:55], v[174:177], v[190:193], v[52:55]
	v_mfma_f32_16x16x32_bf16 v[52:55], v[186:189], v[194:197], v[52:55]
	v_mfma_f32_16x16x32_bf16 v[40:43], v[166:169], v[198:201], v[40:43]
	v_mfma_f32_16x16x32_bf16 v[40:43], v[170:173], v[202:205], v[40:43]
	v_mfma_f32_16x16x32_bf16 v[36:39], v[174:177], v[198:201], v[36:39]
	v_mfma_f32_16x16x32_bf16 v[36:39], v[186:189], v[202:205], v[36:39]
	v_mfma_f32_16x16x32_bf16 v[24:27], v[166:169], v[206:209], v[24:27]
	v_mfma_f32_16x16x32_bf16 v[24:27], v[170:173], v[210:213], v[24:27]
	v_mfma_f32_16x16x32_bf16 v[20:23], v[174:177], v[206:209], v[20:23]
	v_mfma_f32_16x16x32_bf16 v[20:23], v[186:189], v[210:213], v[20:23]
	v_mfma_f32_16x16x32_bf16 v[8:11], v[166:169], v[214:217], v[8:11]
	v_mfma_f32_16x16x32_bf16 v[8:11], v[170:173], v[218:221], v[8:11]
	v_mfma_f32_16x16x32_bf16 v[4:7], v[174:177], v[214:217], v[4:7]
	v_mfma_f32_16x16x32_bf16 v[4:7], v[186:189], v[218:221], v[4:7]
	s_barrier
	s_add_i32 s20, s20, 2
	s_add_u32 s10, s10, 0x100
	s_addc_u32 s11, s11, 0
	s_add_u32 s0, s0, 0x100
	s_addc_u32 s1, s1, 0
	s_cmp_gt_u32 s20, 61
	s_cbranch_scc0 .LBB0_1226
	s_and_b64 vcc, exec, s[48:49]
	s_cbranch_vccz .LBB0_1229
	s_barrier
